# experiment on combo: non-temporal (nt) output stores in the four mixer chains
# speedup vs baseline: 1.0320x; 1.0320x over previous
.LBB0_388:
	v_add_u32_e32 v177, s14, v74
	v_lshl_or_b32 v180, v177, 10, v58
	s_nop 2
	v_cvt_pk_bf16_f32 v52, v172, v173
	v_cvt_pk_bf16_f32 v53, v174, v175
	v_lshl_add_u64 v[54:55], v[180:181], 1, s[10:11]
	global_store_dwordx2 v[54:55], v[52:53], off offset:1536 nt

.LBB0_417:
	v_mul_u32_u24_e32 v98, 0x90, v36
	v_add_u32_e32 v41, s4, v98
	v_lshrrev_b32_e32 v36, 1, v68
	v_readlane_b32 s4, v255, 2
	v_and_or_b32 v99, v36, 24, v37
	s_add_i32 s43, s34, 0
	v_mov_b32_e32 v36, s4
	s_waitcnt lgkmcnt(0)
	s_barrier
	ds_read_b32 v42, v36
	ds_read_b128 v[88:91], v77 offset:9216
	v_mov_b32_e32 v36, s43
	v_mad_u32_u24 v43, v99, s61, v36
	ds_read_b128 v[36:39], v62 offset:64512
	v_add_u32_e32 v84, v43, v50
	ds_read_b64_tr_b16 v[92:93], v84 offset:36864
	ds_read_b64_tr_b16 v[94:95], v84 offset:37440
	ds_read_b128 v[100:103], v78 offset:9216
	v_add_u32_e32 v83, v41, v47
	s_waitcnt lgkmcnt(5)
	v_mul_f32_e32 v41, 0x3fb8aa3b, v42
	v_exp_f32_e32 v41, v41
	s_waitcnt lgkmcnt(3)
	v_mfma_f32_16x16x32_bf16 v[88:91], v[36:39], v[88:91], 0
	ds_read_b128 v[104:107], v62 offset:64576
	ds_read_b128 v[108:111], v77 offset:64512
	v_mul_f32_e32 v112, 0, v41
	v_mov_b32_e32 v113, v112
	s_waitcnt lgkmcnt(2)
	v_mfma_f32_16x16x32_bf16 v[36:39], v[36:39], v[100:103], 0
	ds_read_b128 v[100:103], v78 offset:64512
	v_mov_b32_e32 v114, v112
	v_mov_b32_e32 v115, v112
	ds_read_b128 v[116:119], v83
	ds_read_b64_tr_b16 v[120:121], v84 offset:41472
	ds_read_b128 v[124:127], v77 offset:9280
	s_waitcnt lgkmcnt(4)
	v_mfma_f32_16x16x32_bf16 v[108:111], v[92:95], v[108:111], v[112:115]
	v_mul_lo_u32 v85, v40, s39
	s_add_i32 s44, 0, 0x14400
	s_and_b64 s[4:5], s[26:27], exec
	s_waitcnt lgkmcnt(3)
	v_mfma_f32_16x16x32_bf16 v[100:103], v[92:95], v[100:103], v[112:115]
	ds_read_b64_tr_b16 v[122:123], v84 offset:42048
	ds_read_b128 v[92:95], v78 offset:9280
	s_nop 0
	ds_read_b128 v[112:115], v77 offset:64576
	ds_read_b128 v[128:131], v78 offset:64576
	ds_read_b128 v[132:135], v83 offset:64
	s_cselect_b32 s4, 0xc0, 63
	s_waitcnt lgkmcnt(5)
	v_mfma_f32_16x16x32_bf16 v[124:127], v[104:107], v[124:127], v[88:91]
	s_or_b32 s45, s4, s38
	s_add_i32 s35, s25, 0x900
	s_and_b64 s[4:5], s[26:27], exec
	s_waitcnt lgkmcnt(3)
	v_mfma_f32_16x16x32_bf16 v[104:107], v[104:107], v[92:95], v[36:39]
	v_add_u32_e32 v91, s44, v49
	v_add_u32_e32 v87, s34, v91
	v_add_u32_e32 v93, s44, v48
	s_waitcnt lgkmcnt(2)
	v_mfma_f32_16x16x32_bf16 v[36:39], v[120:123], v[112:115], v[108:111]
	v_add_u32_e32 v87, v87, v46
	v_add_u32_e32 v90, s34, v93
	s_cselect_b32 s4, s92, 0x1b485000
	ds_read_b128 v[108:111], v77 offset:27648
	s_waitcnt lgkmcnt(2)
	v_mfma_f32_16x16x32_bf16 v[40:43], v[120:123], v[128:131], v[100:103]
	s_nop 2
	ds_read_b128 v[100:103], v77 offset:27712
	ds_read_b128 v[112:115], v78 offset:27648
	ds_read_b128 v[120:123], v78 offset:27712
	v_cvt_pk_bf16_f32 v88, v36, v37
	s_waitcnt lgkmcnt(3)
	v_mfma_f32_16x16x32_bf16 v[108:111], v[116:119], v[108:111], v[124:127]
	v_cvt_pk_bf16_f32 v89, v38, v39
	ds_write_b64 v87, v[88:89]
	v_add_u32_e32 v89, s24, v85
	s_waitcnt lgkmcnt(3)
	v_mfma_f32_16x16x32_bf16 v[100:103], v[132:135], v[100:103], v[108:111]
	v_cvt_pk_bf16_f32 v94, v40, v41
	v_cvt_pk_bf16_f32 v95, v42, v43
	v_add_u32_e32 v88, v90, v46
	s_waitcnt lgkmcnt(2)
	v_mfma_f32_16x16x32_bf16 v[104:107], v[116:119], v[112:115], v[104:107]
	v_lshl_or_b32 v89, v89, 10, s33
	v_mul_lo_u32 v86, v86, s39
	s_add_u32 s28, s78, s4
	ds_write_b64 v88, v[94:95]
	v_cvt_pk_bf16_f32 v94, v100, v101
	v_add_u32_e32 v100, s37, v89
	v_mov_b32_e32 v101, v181
	s_addc_u32 s29, s79, 0
	s_waitcnt lgkmcnt(2)
	v_mfma_f32_16x16x32_bf16 v[104:107], v[132:135], v[120:123], v[104:107]
	v_lshl_add_u64 v[100:101], v[100:101], 0, v[180:181]
	v_add_u32_e32 v89, s24, v86
	v_cvt_pk_bf16_f32 v95, v102, v103
	v_lshl_add_u64 v[100:101], v[100:101], 1, s[28:29]
	v_lshl_or_b32 v89, v89, 10, s33
	global_store_dwordx2 v[100:101], v[94:95], off offset:1024 nt
	v_add_u32_e32 v100, s37, v89
	v_mov_b32_e32 v101, v181
	v_lshl_add_u64 v[100:101], v[100:101], 0, v[180:181]
	v_cvt_pk_bf16_f32 v94, v104, v105
	v_cvt_pk_bf16_f32 v95, v106, v107
	v_lshl_add_u64 v[100:101], v[100:101], 1, s[28:29]
	v_mov_b32_e32 v89, v68
	global_store_dwordx2 v[100:101], v[94:95], off offset:1024 nt
	s_waitcnt vmcnt(7)
	v_lshlrev_b32_e32 v94, 16, v4
	v_ashrrev_i32_e32 v90, 3, v89
	v_lshlrev_b32_e32 v89, 4, v89
	v_mul_lo_u32 v92, v90, s61
	v_and_b32_e32 v89, 0x70, v89
	v_add3_u32 v97, 0, v92, v89
	ds_write_b128 v97, v[16:19]
	v_lshl_add_u32 v16, v90, 2, 0
	v_add_u32_e32 v16, 0x1fa00, v16
	ds_read_b32 v112, v16
	v_and_b32_e32 v95, 0xffff0000, v4
	v_and_b32_e32 v17, 0xffff0000, v12
	v_lshlrev_b32_e32 v104, 16, v5
	v_and_b32_e32 v105, 0xffff0000, v5
	s_waitcnt lgkmcnt(0)
	v_mul_f32_e32 v16, 0x3fb8aa3b, v112
	v_exp_f32_e32 v90, v16
	v_lshlrev_b32_e32 v16, 16, v12
	v_lshlrev_b32_e32 v108, 16, v15
	v_and_b32_e32 v109, 0xffff0000, v15
	v_pk_mul_f32 v[18:19], v[90:91], v[94:95] op_sel_hi:[0,1]
	v_cvt_pk_bf16_f32 v100, v18, v19
	v_lshlrev_b32_e32 v18, 16, v13
	v_and_b32_e32 v19, 0xffff0000, v13
	v_pk_mul_f32 v[16:17], v[90:91], v[16:17] op_sel_hi:[0,1]
	v_pk_mul_f32 v[18:19], v[90:91], v[18:19] op_sel_hi:[0,1]
	v_cvt_pk_bf16_f32 v16, v16, v17
	v_cvt_pk_bf16_f32 v17, v18, v19
	v_pk_mul_f32 v[18:19], v[90:91], v[104:105] op_sel_hi:[0,1]
	v_cvt_pk_bf16_f32 v101, v18, v19
	v_lshlrev_b32_e32 v18, 16, v14
	v_and_b32_e32 v19, 0xffff0000, v14
	v_pk_mul_f32 v[18:19], v[90:91], v[18:19] op_sel_hi:[0,1]
	v_pk_mul_f32 v[108:109], v[90:91], v[108:109] op_sel_hi:[0,1]
	v_cvt_pk_bf16_f32 v18, v18, v19
	v_lshlrev_b32_e32 v106, 16, v6
	v_and_b32_e32 v107, 0xffff0000, v6
	v_cvt_pk_bf16_f32 v19, v108, v109
	v_lshlrev_b32_e32 v108, 16, v7
	v_and_b32_e32 v109, 0xffff0000, v7
	v_readlane_b32 s4, v255, 4
	v_pk_mul_f32 v[102:103], v[90:91], v[106:107] op_sel_hi:[0,1]
	v_pk_mul_f32 v[110:111], v[90:91], v[108:109] op_sel_hi:[0,1]
	v_add3_u32 v90, s4, v92, v89
	v_cvt_pk_bf16_f32 v102, v102, v103
	v_cvt_pk_bf16_f32 v103, v110, v111
	ds_write_b128 v90, v[16:19]
	ds_write_b128 v97, v[100:103] offset:18432
	v_add3_u32 v16, s40, v92, v89
	ds_write_b128 v16, v[12:15]
	v_add3_u32 v12, s41, v92, v89
	ds_write_b128 v12, v[4:7]
	s_waitcnt vmcnt(6)
	ds_write_b128 v97, v[8:11] offset:46080
	v_mov_b32_e32 v4, s72
	ds_read_b32 v4, v4
	v_readlane_b32 s4, v255, 6
	s_waitcnt lgkmcnt(0)
	v_sub_f32_e32 v4, v4, v112
	v_mul_f32_e32 v4, 0x3fb8aa3b, v4
	v_exp_f32_e32 v8, v4
	s_nop 0
	v_pk_mul_f32 v[4:5], v[8:9], v[94:95] op_sel_hi:[0,1]
	v_pk_mul_f32 v[6:7], v[8:9], v[104:105] op_sel_hi:[0,1]
	v_cvt_pk_bf16_f32 v4, v4, v5
	v_cvt_pk_bf16_f32 v5, v6, v7
	v_pk_mul_f32 v[6:7], v[8:9], v[106:107] op_sel_hi:[0,1]
	v_pk_mul_f32 v[8:9], v[8:9], v[108:109] op_sel_hi:[0,1]
	v_cvt_pk_bf16_f32 v6, v6, v7
	v_cvt_pk_bf16_f32 v7, v8, v9
	v_add3_u32 v8, s4, v92, v89
	ds_write_b128 v8, v[4:7]
	v_mov_b32_e32 v4, v68
	s_and_b64 s[4:5], s[26:27], exec
	s_waitcnt lgkmcnt(0)
	s_barrier
	s_cselect_b32 s4, 0xc0, 0
	v_ashrrev_i32_e32 v6, 3, v4
	s_or_b32 s24, s4, s38
	v_lshlrev_b32_e32 v4, 3, v4
	v_add_u32_e32 v5, s24, v6
	v_and_b32_e32 v7, 56, v4
	v_mul_lo_u32 v6, v6, s39
	v_or_b32_e32 v4, s35, v7
	v_add_u32_e32 v6, s45, v6
	v_or_b32_e32 v4, s0, v4
	v_mul_u32_u24_e32 v6, 0x300, v6
	v_mad_u32_u24 v4, v5, s63, v4
	v_or3_b32 v6, v6, s37, v7
	v_ashrrev_i32_e32 v5, 31, v4
	v_ashrrev_i32_e32 v7, 31, v6
	v_lshl_add_u64 v[4:5], v[4:5], 1, s[82:83]
	v_lshl_add_u64 v[16:17], v[6:7], 1, s[84:85]
	global_load_dwordx4 v[4:7], v[4:5], off
	s_nop 0
	global_load_dwordx4 v[8:11], v[16:17], off
	global_load_dwordx4 v[12:15], v[16:17], off offset:512
	s_nop 0
	global_load_dwordx4 v[16:19], v[16:17], off offset:1024
	v_or_b32_e32 v89, 8, v59
	s_and_saveexec_b64 s[4:5], s[6:7]
	s_cbranch_execz .LBB0_419
	v_add_u32_e32 v55, s24, v68
	v_lshl_add_u32 v94, v55, 4, v59
	v_mov_b32_e32 v95, v181
	v_lshl_add_u64 v[94:95], v[94:95], 2, s[86:87]
	v_add_u32_e32 v58, s45, v54
	global_load_dword v55, v[94:95], off
	v_lshl_add_u32 v94, v58, 4, v89
	v_mov_b32_e32 v95, v181
	v_lshl_add_u64 v[94:95], v[94:95], 2, s[86:87]
	global_load_dword v58, v[94:95], off

.LBB0_423:
	v_mov_b32_e32 v53, s72
	s_waitcnt lgkmcnt(0)
	s_barrier
	ds_read_b32 v53, v53
	v_mul_u32_u24_e32 v52, 0x90, v99
	v_add_u32_e32 v51, s44, v98
	s_add_i32 s43, s43, 0x1d400
	v_add_u32_e32 v99, s43, v52
	v_add_u32_e32 v98, v51, v47
	v_add_u32_e32 v100, s43, v50
	ds_read_b128 v[104:107], v98
	s_waitcnt lgkmcnt(1)
	v_mul_f32_e32 v51, 0x3fb8aa3b, v53
	v_add_u32_e32 v99, v99, v50
	v_exp_f32_e32 v102, v51
	ds_read_b128 v[108:111], v62 offset:64512
	ds_read_b128 v[112:115], v62 offset:64576
	ds_read_b64_tr_b16 v[50:51], v99
	v_add_u32_e32 v100, v100, v52
	ds_read_b128 v[116:119], v77 offset:9216
	ds_read_b64_tr_b16 v[52:53], v99 offset:576
	ds_read_b64_tr_b16 v[120:121], v100 offset:4608
	ds_read_b64_tr_b16 v[122:123], v100 offset:5184
	ds_read_b128 v[124:127], v77 offset:9280
	ds_read_b128 v[128:131], v78 offset:9216
	s_waitcnt lgkmcnt(5)
	v_mfma_f32_16x16x32_bf16 v[116:119], v[108:111], v[116:119], 0
	ds_read_b128 v[132:135], v78 offset:9280
	ds_read_b128 v[136:139], v77 offset:64512
	ds_read_b128 v[140:143], v77 offset:64576
	v_readlane_b32 s4, v255, 4
	v_pk_mul_f32 v[38:39], v[38:39], v[102:103] op_sel_hi:[1,0]
	s_waitcnt lgkmcnt(3)
	v_mfma_f32_16x16x32_bf16 v[108:111], v[108:111], v[128:131], 0
	ds_read_b128 v[128:131], v78 offset:64512
	v_add_u32_e32 v49, s4, v49
	v_pk_mul_f32 v[36:37], v[36:37], v[102:103] op_sel_hi:[1,0]
	v_pk_mul_f32 v[42:43], v[42:43], v[102:103] op_sel_hi:[1,0]
	v_pk_mul_f32 v[40:41], v[40:41], v[102:103] op_sel_hi:[1,0]
	v_add_u32_e32 v101, v49, v47
	s_waitcnt lgkmcnt(2)
	v_mfma_f32_16x16x32_bf16 v[36:39], v[50:53], v[136:139], v[36:39]
	ds_read_b128 v[136:139], v78 offset:64576
	v_add_u32_e32 v48, s4, v48
	v_add_u32_e32 v102, v48, v47
	s_waitcnt lgkmcnt(1)
	v_mfma_f32_16x16x32_bf16 v[40:43], v[50:53], v[128:131], v[40:43]
	v_add_u32_e32 v47, s34, v44
	v_add_u32_e32 v103, v47, v46
	v_mov_b32_e32 v47, v181
	v_mfma_f32_16x16x32_bf16 v[50:53], v[112:115], v[124:127], v[116:119]
	v_mfma_f32_16x16x32_bf16 v[108:111], v[112:115], v[132:135], v[108:111]
	ds_read_b128 v[112:115], v101
	s_nop 0
	ds_read_b128 v[116:119], v101 offset:64
	v_mfma_f32_16x16x32_bf16 v[36:39], v[120:123], v[140:143], v[36:39]
	s_waitcnt lgkmcnt(2)
	v_mfma_f32_16x16x32_bf16 v[40:43], v[120:123], v[136:139], v[40:43]
	s_waitcnt lgkmcnt(1)
	v_mfma_f32_16x16x32_bf16 v[48:51], v[104:107], v[112:115], v[50:53]
	ds_read_b128 v[112:115], v102
	ds_read_b128 v[120:123], v102 offset:64
	s_nop 1
	v_cvt_pk_bf16_f32 v44, v36, v37
	v_add_u32_e32 v52, s34, v45
	s_waitcnt lgkmcnt(1)
	v_mfma_f32_16x16x32_bf16 v[104:107], v[104:107], v[112:115], v[108:111]
	v_cvt_pk_bf16_f32 v45, v38, v39
	s_waitcnt vmcnt(7)
	v_and_b32_e32 v53, 0xffff0000, v21
	ds_read_b128 v[108:111], v98 offset:64
	s_waitcnt lgkmcnt(0)
	v_mfma_f32_16x16x32_bf16 v[48:51], v[108:111], v[116:119], v[48:51]
	ds_write_b64 v103, v[44:45]
	v_cvt_pk_bf16_f32 v44, v40, v41
	v_cvt_pk_bf16_f32 v45, v42, v43
	v_mfma_f32_16x16x32_bf16 v[106:109], v[108:111], v[120:123], v[104:107]
	s_nop 2
	v_add_u32_e32 v104, v52, v46
	ds_write_b64 v104, v[44:45]
	v_add_u32_e32 v44, s2, v85
	v_lshl_or_b32 v46, v44, 10, s33
	v_add_u32_e32 v46, s37, v46
	v_lshl_add_u64 v[46:47], v[46:47], 0, v[180:181]
	v_cvt_pk_bf16_f32 v44, v48, v49
	v_cvt_pk_bf16_f32 v45, v50, v51
	v_lshl_add_u64 v[46:47], v[46:47], 1, s[28:29]
	global_store_dwordx2 v[46:47], v[44:45], off offset:1024 nt
	v_add_u32_e32 v44, s2, v86
	v_lshl_or_b32 v46, v44, 10, s33
	v_add_u32_e32 v46, s37, v46
	v_mov_b32_e32 v47, v181
	v_lshl_add_u64 v[46:47], v[46:47], 0, v[180:181]
	v_cvt_pk_bf16_f32 v44, v106, v107
	v_cvt_pk_bf16_f32 v45, v108, v109
	v_lshl_add_u64 v[46:47], v[46:47], 1, s[28:29]
	global_store_dwordx2 v[46:47], v[44:45], off offset:1024 nt
	v_mov_b32_e32 v44, v68
	v_lshlrev_b32_e32 v50, 16, v20
	v_ashrrev_i32_e32 v45, 3, v44
	v_lshlrev_b32_e32 v44, 4, v44
	v_mul_lo_u32 v105, v45, s61
	v_and_b32_e32 v110, 0x70, v44
	v_add3_u32 v111, 0, v105, v110
	ds_write_b128 v111, v[32:35]
	v_lshl_add_u32 v32, v45, 2, 0
	v_add_u32_e32 v32, 0x1f800, v32
	ds_read_b32 v112, v32
	v_and_b32_e32 v51, 0xffff0000, v20
	v_and_b32_e32 v33, 0xffff0000, v28
	v_lshlrev_b32_e32 v52, 16, v21
	v_lshlrev_b32_e32 v108, 16, v31
	s_waitcnt lgkmcnt(0)
	v_mul_f32_e32 v32, 0x3fb8aa3b, v112
	v_exp_f32_e32 v48, v32
	v_lshlrev_b32_e32 v32, 16, v28
	v_and_b32_e32 v109, 0xffff0000, v31
	v_lshlrev_b32_e32 v106, 16, v22
	v_pk_mul_f32 v[34:35], v[48:49], v[50:51] op_sel_hi:[0,1]
	v_cvt_pk_bf16_f32 v44, v34, v35
	v_lshlrev_b32_e32 v34, 16, v29
	v_and_b32_e32 v35, 0xffff0000, v29
	v_pk_mul_f32 v[32:33], v[48:49], v[32:33] op_sel_hi:[0,1]
	v_pk_mul_f32 v[34:35], v[48:49], v[34:35] op_sel_hi:[0,1]
	v_cvt_pk_bf16_f32 v32, v32, v33
	v_cvt_pk_bf16_f32 v33, v34, v35
	v_pk_mul_f32 v[34:35], v[48:49], v[52:53] op_sel_hi:[0,1]
	v_cvt_pk_bf16_f32 v45, v34, v35
	v_lshlrev_b32_e32 v34, 16, v30
	v_and_b32_e32 v35, 0xffff0000, v30
	v_pk_mul_f32 v[34:35], v[48:49], v[34:35] op_sel_hi:[0,1]
	v_pk_mul_f32 v[108:109], v[48:49], v[108:109] op_sel_hi:[0,1]
	v_cvt_pk_bf16_f32 v34, v34, v35
	v_and_b32_e32 v107, 0xffff0000, v22
	v_cvt_pk_bf16_f32 v35, v108, v109
	v_lshlrev_b32_e32 v108, 16, v23
	v_and_b32_e32 v109, 0xffff0000, v23
	v_pk_mul_f32 v[46:47], v[48:49], v[106:107] op_sel_hi:[0,1]
	v_pk_mul_f32 v[48:49], v[48:49], v[108:109] op_sel_hi:[0,1]
	v_cvt_pk_bf16_f32 v46, v46, v47
	v_cvt_pk_bf16_f32 v47, v48, v49
	ds_write_b128 v111, v[32:35] offset:27648
	ds_write_b128 v111, v[44:47] offset:18432
	v_add3_u32 v32, s40, v105, v110
	ds_write_b128 v32, v[28:31]
	v_add3_u32 v28, s41, v105, v110
	v_readlane_b32 s2, v255, 2
	ds_write_b128 v28, v[20:23]
	s_waitcnt vmcnt(8)
	ds_write_b128 v111, v[24:27] offset:46080
	v_mov_b32_e32 v20, s2
	ds_read_b32 v20, v20
	s_lshl_b32 s2, s1, 12
	s_or_b32 s1, s2, 0x800
	s_or_b32 s2, s2, 0x700
	s_and_b64 s[4:5], s[26:27], exec
	s_waitcnt lgkmcnt(0)
	v_sub_f32_e32 v20, v20, v112
	v_mul_f32_e32 v20, 0x3fb8aa3b, v20
	v_exp_f32_e32 v24, v20
	s_movk_i32 s4, 0x10c0
	s_cselect_b32 s4, 0x100, s4
	s_add_i32 s31, s2, s4
	v_pk_mul_f32 v[20:21], v[24:25], v[50:51] op_sel_hi:[0,1]
	v_pk_mul_f32 v[22:23], v[24:25], v[52:53] op_sel_hi:[0,1]
	v_cvt_pk_bf16_f32 v20, v20, v21
	v_cvt_pk_bf16_f32 v21, v22, v23
	v_pk_mul_f32 v[22:23], v[24:25], v[106:107] op_sel_hi:[0,1]
	v_pk_mul_f32 v[24:25], v[24:25], v[108:109] op_sel_hi:[0,1]
	v_cvt_pk_bf16_f32 v22, v22, v23
	v_cvt_pk_bf16_f32 v23, v24, v25
	ds_write_b128 v111, v[20:23] offset:36864
	v_mov_b32_e32 v20, v68
	s_waitcnt lgkmcnt(0)
	s_barrier
	s_and_b64 s[4:5], s[26:27], exec
	v_ashrrev_i32_e32 v22, 3, v20
	s_cselect_b32 s4, 0, 0xfff
	v_lshlrev_b32_e32 v20, 3, v20
	s_add_i32 s30, s1, s4
	v_add_u32_e32 v21, s31, v22
	v_and_b32_e32 v23, 56, v20
	v_mul_lo_u32 v22, v22, s39
	v_or_b32_e32 v20, s35, v23
	v_add_u32_e32 v22, s30, v22
	v_or_b32_e32 v20, s0, v20
	v_mul_u32_u24_e32 v22, 0x300, v22
	v_mad_u32_u24 v20, v21, s63, v20
	v_or3_b32 v22, v22, s37, v23
	v_ashrrev_i32_e32 v21, 31, v20
	v_ashrrev_i32_e32 v23, 31, v22
	v_lshl_add_u64 v[20:21], v[20:21], 1, s[82:83]
	v_lshl_add_u64 v[32:33], v[22:23], 1, s[84:85]
	global_load_dwordx4 v[20:23], v[20:21], off
	s_nop 0
	global_load_dwordx4 v[24:27], v[32:33], off
	global_load_dwordx4 v[28:31], v[32:33], off offset:512
	s_nop 0
	global_load_dwordx4 v[32:35], v[32:33], off offset:1024
	s_and_saveexec_b64 s[4:5], s[6:7]
	s_cbranch_execz .LBB0_425
	v_add_u32_e32 v44, s31, v68
	v_lshl_add_u32 v44, v44, 4, v59
	v_mov_b32_e32 v45, v181
	v_lshl_add_u64 v[44:45], v[44:45], 2, s[86:87]
	global_load_dword v56, v[44:45], off
	v_add_u32_e32 v44, s30, v54
	v_lshl_add_u32 v44, v44, 4, v89
	v_mov_b32_e32 v45, v181
	v_lshl_add_u64 v[44:45], v[44:45], 2, s[86:87]
	global_load_dword v57, v[44:45], off

.LBB0_436:
	v_add_u32_e32 v105, s34, v85
	v_cvt_pk_bf16_f32 v48, v48, v49
	v_cvt_pk_bf16_f32 v49, v50, v51
	v_lshl_or_b32 v50, v105, 10, v52
	v_mov_b32_e32 v51, v53
	v_lshl_add_u64 v[50:51], v[50:51], 1, s[28:29]
	global_store_dwordx2 v[50:51], v[48:49], off offset:1024 nt
	v_add_u32_e32 v48, s34, v86
	v_cvt_pk_bf16_f32 v44, v44, v45
	v_cvt_pk_bf16_f32 v45, v46, v47
	v_lshl_or_b32 v46, v48, 10, v52
	v_mov_b32_e32 v47, v53
	v_lshl_add_u64 v[46:47], v[46:47], 1, s[28:29]
	global_store_dwordx2 v[46:47], v[44:45], off offset:1024 nt
	v_mov_b32_e32 v44, v68
	s_waitcnt vmcnt(5)
	v_lshlrev_b32_e32 v108, 16, v12
	v_ashrrev_i32_e32 v45, 3, v44
	v_lshlrev_b32_e32 v44, 4, v44
	v_mul_lo_u32 v105, v45, s61
	v_and_b32_e32 v116, 0x70, v44
	v_add3_u32 v117, 0, v105, v116
	v_lshl_add_u32 v44, v45, 2, 0
	ds_write_b128 v117, v[4:7]
	v_add_u32_e32 v44, 0x1fa00, v44
	ds_read_b32 v118, v44
	v_and_b32_e32 v109, 0xffff0000, v12
	v_and_b32_e32 v45, 0xffff0000, v8
	v_lshlrev_b32_e32 v110, 16, v13
	v_and_b32_e32 v111, 0xffff0000, v13
	s_waitcnt lgkmcnt(0)
	v_mul_f32_e32 v44, 0x3fb8aa3b, v118
	v_exp_f32_e32 v106, v44
	v_lshlrev_b32_e32 v44, 16, v8
	v_lshlrev_b32_e32 v114, 16, v11
	v_and_b32_e32 v115, 0xffff0000, v11
	v_pk_mul_f32 v[46:47], v[106:107], v[108:109] op_sel_hi:[0,1]
	v_cvt_pk_bf16_f32 v48, v46, v47
	v_lshlrev_b32_e32 v46, 16, v9
	v_and_b32_e32 v47, 0xffff0000, v9
	v_pk_mul_f32 v[44:45], v[106:107], v[44:45] op_sel_hi:[0,1]
	v_pk_mul_f32 v[46:47], v[106:107], v[46:47] op_sel_hi:[0,1]
	v_cvt_pk_bf16_f32 v44, v44, v45
	v_cvt_pk_bf16_f32 v45, v46, v47
	v_pk_mul_f32 v[46:47], v[106:107], v[110:111] op_sel_hi:[0,1]
	v_cvt_pk_bf16_f32 v49, v46, v47
	v_lshlrev_b32_e32 v46, 16, v10
	v_and_b32_e32 v47, 0xffff0000, v10
	v_pk_mul_f32 v[46:47], v[106:107], v[46:47] op_sel_hi:[0,1]
	v_pk_mul_f32 v[114:115], v[106:107], v[114:115] op_sel_hi:[0,1]
	v_cvt_pk_bf16_f32 v46, v46, v47
	v_lshlrev_b32_e32 v112, 16, v14
	v_and_b32_e32 v113, 0xffff0000, v14
	v_cvt_pk_bf16_f32 v47, v114, v115
	v_lshlrev_b32_e32 v114, 16, v15
	v_and_b32_e32 v115, 0xffff0000, v15
	v_pk_mul_f32 v[50:51], v[106:107], v[112:113] op_sel_hi:[0,1]
	v_pk_mul_f32 v[106:107], v[106:107], v[114:115] op_sel_hi:[0,1]
	v_readlane_b32 s4, v255, 4
	v_cvt_pk_bf16_f32 v50, v50, v51
	v_cvt_pk_bf16_f32 v51, v106, v107
	v_add3_u32 v106, s4, v105, v116
	ds_write_b128 v106, v[44:47]
	ds_write_b128 v117, v[48:51] offset:18432
	v_add3_u32 v44, s40, v105, v116
	ds_write_b128 v44, v[8:11]
	v_add3_u32 v44, s41, v105, v116
	ds_write_b128 v44, v[12:15]
	s_waitcnt vmcnt(4)
	ds_write_b128 v117, v[16:19] offset:46080
	v_mov_b32_e32 v44, s72
	ds_read_b32 v44, v44
	v_readlane_b32 s4, v255, 6
	s_cmp_gt_u32 s45, 64
	s_waitcnt lgkmcnt(0)
	v_sub_f32_e32 v44, v44, v118
	v_mul_f32_e32 v44, 0x3fb8aa3b, v44
	v_exp_f32_e32 v48, v44
	s_nop 0
	v_pk_mul_f32 v[44:45], v[48:49], v[108:109] op_sel_hi:[0,1]
	v_pk_mul_f32 v[46:47], v[48:49], v[110:111] op_sel_hi:[0,1]
	v_cvt_pk_bf16_f32 v44, v44, v45
	v_cvt_pk_bf16_f32 v45, v46, v47
	v_pk_mul_f32 v[46:47], v[48:49], v[112:113] op_sel_hi:[0,1]
	v_pk_mul_f32 v[48:49], v[48:49], v[114:115] op_sel_hi:[0,1]
	v_cvt_pk_bf16_f32 v46, v46, v47
	v_cvt_pk_bf16_f32 v47, v48, v49
	v_add3_u32 v48, s4, v105, v116
	ds_write_b128 v48, v[44:47]
	s_waitcnt lgkmcnt(0)
	s_barrier
	s_cbranch_scc1 .Lgdn_skipA
	s_and_b64 s[4:5], s[26:27], exec
	s_cselect_b32 s4, s43, s44
	s_lshl_b32 s35, s4, 6
	s_add_i32 s35, s35, s2
	s_add_i32 s34, s33, 64
	v_mov_b32_e32 v4, v68
	s_and_b64 s[4:5], s[26:27], exec
	s_cselect_b32 s34, s42, s34
	v_ashrrev_i32_e32 v6, 3, v4
	s_add_i32 s34, s34, s1
	v_add_u32_e32 v5, s35, v6
	v_lshlrev_b32_e32 v4, 3, v4
	v_mul_lo_u32 v6, v6, s39
	v_and_b32_e32 v7, 56, v4
	v_add_u32_e32 v6, s34, v6
	v_or_b32_e32 v4, s0, v7
	v_mul_u32_u24_e32 v6, 0x300, v6
	v_mad_u32_u24 v4, v5, s63, v4
	v_or3_b32 v6, v6, s37, v7
	v_ashrrev_i32_e32 v5, 31, v4
	v_ashrrev_i32_e32 v7, 31, v6
	v_lshl_add_u64 v[4:5], v[4:5], 1, s[82:83]
	v_lshl_add_u64 v[16:17], v[6:7], 1, s[84:85]
	global_load_dwordx4 v[4:7], v[4:5], off
	s_nop 0
	global_load_dwordx4 v[8:11], v[16:17], off
	global_load_dwordx4 v[12:15], v[16:17], off offset:512
	s_nop 0
	global_load_dwordx4 v[16:19], v[16:17], off offset:1024
	s_and_saveexec_b64 s[4:5], s[6:7]
	s_cbranch_execz .LBB0_439
	v_add_u32_e32 v44, s35, v68
	v_lshl_add_u32 v180, v44, 4, v59
	v_lshl_add_u64 v[44:45], v[180:181], 2, s[86:87]
	global_load_dword v55, v[44:45], off
	v_add_u32_e32 v44, s34, v54
	v_lshl_add_u32 v180, v44, 4, v89
	v_lshl_add_u64 v[44:45], v[180:181], 2, s[86:87]
	global_load_dword v58, v[44:45], off

.LBB0_448:
	v_add_u32_e32 v105, s30, v85
	v_cvt_pk_bf16_f32 v48, v48, v49
	v_cvt_pk_bf16_f32 v49, v50, v51
	v_lshl_or_b32 v50, v105, 10, v52
	v_mov_b32_e32 v51, v53
	v_lshl_add_u64 v[50:51], v[50:51], 1, s[28:29]
	global_store_dwordx2 v[50:51], v[48:49], off offset:1024 nt
	v_add_u32_e32 v48, s30, v86
	v_cvt_pk_bf16_f32 v44, v44, v45
	v_cvt_pk_bf16_f32 v45, v46, v47
	v_lshl_or_b32 v46, v48, 10, v52
	v_mov_b32_e32 v47, v53
	v_lshl_add_u64 v[46:47], v[46:47], 1, s[28:29]
	s_andn2_b64 vcc, exec, s[34:35]
	global_store_dwordx2 v[46:47], v[44:45], off offset:1024 nt
	s_cbranch_vccnz .LBB0_450
	v_mov_b32_e32 v44, v68
	s_waitcnt vmcnt(5)
	v_lshlrev_b32_e32 v108, 16, v28
	v_ashrrev_i32_e32 v45, 3, v44
	v_lshlrev_b32_e32 v44, 4, v44
	v_mul_lo_u32 v105, v45, s61
	v_and_b32_e32 v116, 0x70, v44
	v_add3_u32 v117, 0, v105, v116
	v_lshl_add_u32 v44, v45, 2, 0
	ds_write_b128 v117, v[20:23]
	v_add_u32_e32 v44, 0x1f800, v44
	ds_read_b32 v118, v44
	v_and_b32_e32 v109, 0xffff0000, v28
	v_and_b32_e32 v45, 0xffff0000, v24
	v_lshlrev_b32_e32 v110, 16, v29
	v_and_b32_e32 v111, 0xffff0000, v29
	s_waitcnt lgkmcnt(0)
	v_mul_f32_e32 v44, 0x3fb8aa3b, v118
	v_exp_f32_e32 v106, v44
	v_lshlrev_b32_e32 v44, 16, v24
	v_lshlrev_b32_e32 v114, 16, v27
	v_and_b32_e32 v115, 0xffff0000, v27
	v_pk_mul_f32 v[46:47], v[106:107], v[108:109] op_sel_hi:[0,1]
	v_cvt_pk_bf16_f32 v48, v46, v47
	v_lshlrev_b32_e32 v46, 16, v25
	v_and_b32_e32 v47, 0xffff0000, v25
	v_pk_mul_f32 v[44:45], v[106:107], v[44:45] op_sel_hi:[0,1]
	v_pk_mul_f32 v[46:47], v[106:107], v[46:47] op_sel_hi:[0,1]
	v_cvt_pk_bf16_f32 v44, v44, v45
	v_cvt_pk_bf16_f32 v45, v46, v47
	v_pk_mul_f32 v[46:47], v[106:107], v[110:111] op_sel_hi:[0,1]
	v_cvt_pk_bf16_f32 v49, v46, v47
	v_lshlrev_b32_e32 v46, 16, v26
	v_and_b32_e32 v47, 0xffff0000, v26
	v_pk_mul_f32 v[46:47], v[106:107], v[46:47] op_sel_hi:[0,1]
	v_pk_mul_f32 v[114:115], v[106:107], v[114:115] op_sel_hi:[0,1]
	v_cvt_pk_bf16_f32 v46, v46, v47
	v_lshlrev_b32_e32 v112, 16, v30
	v_and_b32_e32 v113, 0xffff0000, v30
	v_cvt_pk_bf16_f32 v47, v114, v115
	v_lshlrev_b32_e32 v114, 16, v31
	v_and_b32_e32 v115, 0xffff0000, v31
	v_pk_mul_f32 v[50:51], v[106:107], v[112:113] op_sel_hi:[0,1]
	v_pk_mul_f32 v[106:107], v[106:107], v[114:115] op_sel_hi:[0,1]
	v_cvt_pk_bf16_f32 v50, v50, v51
	v_cvt_pk_bf16_f32 v51, v106, v107
	ds_write_b128 v117, v[44:47] offset:27648
	ds_write_b128 v117, v[48:51] offset:18432
	v_add3_u32 v44, s40, v105, v116
	ds_write_b128 v44, v[24:27]
	v_add3_u32 v44, s41, v105, v116
	v_readlane_b32 s4, v255, 2
	ds_write_b128 v44, v[28:31]
	s_waitcnt vmcnt(4)
	ds_write_b128 v117, v[32:35] offset:46080
	v_mov_b32_e32 v44, s4
	ds_read_b32 v44, v44
	s_waitcnt lgkmcnt(0)
	v_sub_f32_e32 v44, v44, v118
	v_mul_f32_e32 v44, 0x3fb8aa3b, v44
	v_exp_f32_e32 v48, v44
	s_nop 0
	v_pk_mul_f32 v[44:45], v[48:49], v[108:109] op_sel_hi:[0,1]
	v_pk_mul_f32 v[46:47], v[48:49], v[110:111] op_sel_hi:[0,1]
	v_cvt_pk_bf16_f32 v44, v44, v45
	v_cvt_pk_bf16_f32 v45, v46, v47
	v_pk_mul_f32 v[46:47], v[48:49], v[112:113] op_sel_hi:[0,1]
	v_pk_mul_f32 v[48:49], v[48:49], v[114:115] op_sel_hi:[0,1]
	v_cvt_pk_bf16_f32 v46, v46, v47
	v_cvt_pk_bf16_f32 v47, v48, v49
	ds_write_b128 v117, v[44:47] offset:36864

.LBB0_480:
	ds_read_b64_tr_b16 v[40:41], v104 offset:27648
	ds_read_b64_tr_b16 v[42:43], v104 offset:28224
	v_exp_f32_e32 v60, v118
	ds_read_b128 v[44:47], v109 offset:36864
	v_exp_f32_e32 v61, v119
	v_exp_f32_e32 v62, v120
	v_exp_f32_e32 v63, v121
	ds_read_b128 v[36:39], v108 offset:36864
	s_waitcnt lgkmcnt(1)
	v_mfma_f32_16x16x32_bf16 v[44:47], v[40:43], v[44:47], 0
	ds_read_b64_tr_b16 v[48:49], v104 offset:18432
	ds_read_b64_tr_b16 v[50:51], v104 offset:19008
	ds_read_b64_tr_b16 v[52:53], v104 offset:32256
	v_pk_mul_f32 v[34:35], v[34:35], v[62:63]
	v_pk_mul_f32 v[32:33], v[32:33], v[60:61]
	s_waitcnt lgkmcnt(3)
	v_mfma_f32_16x16x32_bf16 v[36:39], v[40:43], v[36:39], 0
	ds_read_b64_tr_b16 v[40:41], v106 offset:27648
	ds_read_b64_tr_b16 v[42:43], v106 offset:28224
	ds_read_b64_tr_b16 v[56:57], v107 offset:27648
	ds_read_b64_tr_b16 v[58:59], v107 offset:28224
	ds_read_b64_tr_b16 v[54:55], v104 offset:32832
	v_pk_mul_f32 v[30:31], v[30:31], v[62:63]
	v_pk_mul_f32 v[28:29], v[28:29], v[60:61]
	s_waitcnt lgkmcnt(3)
	v_mfma_f32_16x16x32_bf16 v[32:35], v[48:51], v[40:43], v[32:35]
	s_add_i32 s47, s47, 2
	s_and_b64 vcc, exec, s[60:61]
	s_mov_b32 s60, 0xffff0000
	s_waitcnt lgkmcnt(1)
	v_mfma_f32_16x16x32_bf16 v[40:43], v[48:51], v[56:59], v[28:31]
	s_nop 2
	ds_read_b128 v[28:31], v109 offset:36928
	ds_read_b64_tr_b16 v[48:49], v104 offset:23616
	ds_read_b128 v[56:59], v108 offset:36928
	s_movk_i32 s61, 0x90
	s_waitcnt lgkmcnt(2)
	v_mfma_f32_16x16x32_bf16 v[60:63], v[52:55], v[28:31], v[44:47]
	s_nop 2
	ds_read_b64_tr_b16 v[46:47], v104 offset:23040
	ds_read_b64_tr_b16 v[28:29], v106 offset:32256
	s_waitcnt lgkmcnt(2)
	v_mfma_f32_16x16x32_bf16 v[36:39], v[52:55], v[56:59], v[36:39]
	ds_read_b64_tr_b16 v[30:31], v106 offset:32832
	ds_read_b64_tr_b16 v[50:51], v107 offset:32256
	ds_read_b64_tr_b16 v[52:53], v107 offset:32832
	ds_read_b128 v[54:57], v105 offset:55296
	s_waitcnt lgkmcnt(3)
	v_mfma_f32_16x16x32_bf16 v[28:31], v[46:49], v[28:31], v[32:35]
	s_waitcnt lgkmcnt(1)
	v_mfma_f32_16x16x32_bf16 v[32:35], v[46:49], v[50:53], v[40:43]
	s_nop 2
	ds_read_b128 v[40:43], v109 offset:9216
	ds_read_b128 v[44:47], v108 offset:9216
	ds_read_b128 v[48:51], v105 offset:55360
	v_cvt_pk_bf16_f32 v52, v28, v29
	s_waitcnt lgkmcnt(1)
	v_mfma_f32_16x16x32_bf16 v[36:39], v[54:57], v[44:47], v[36:39]
	ds_read_b128 v[44:47], v109 offset:9280
	v_cvt_pk_bf16_f32 v53, v30, v31
	v_mfma_f32_16x16x32_bf16 v[40:43], v[54:57], v[40:43], v[60:63]
	s_waitcnt lgkmcnt(0)
	v_mfma_f32_16x16x32_bf16 v[40:43], v[48:51], v[44:47], v[40:43]
	ds_read_b128 v[44:47], v108 offset:9280
	ds_write_b64 v113, v[52:53] offset:46080
	s_waitcnt lgkmcnt(1)
	v_mfma_f32_16x16x32_bf16 v[36:39], v[48:51], v[44:47], v[36:39]
	v_cvt_pk_bf16_f32 v44, v32, v33
	v_cvt_pk_bf16_f32 v45, v34, v35
	ds_write_b64 v112, v[44:45] offset:46080
	v_add_u32_e32 v44, s34, v75
	v_lshl_or_b32 v180, v44, 10, v76
	v_cvt_pk_bf16_f32 v40, v40, v41
	v_cvt_pk_bf16_f32 v41, v42, v43
	v_lshl_add_u64 v[42:43], v[180:181], 1, s[92:93]
	global_store_dwordx2 v[42:43], v[40:41], off nt
	v_add_u32_e32 v40, s34, v77
	v_lshl_or_b32 v180, v40, 10, v76
	v_cvt_pk_bf16_f32 v36, v36, v37
	v_cvt_pk_bf16_f32 v37, v38, v39
	v_lshl_add_u64 v[38:39], v[180:181], 1, s[92:93]
	global_store_dwordx2 v[38:39], v[36:37], off nt
	s_waitcnt lgkmcnt(0)
	s_barrier
	s_cbranch_vccnz .LBB0_541

.LBB0_508:
	v_add_u32_e32 v109, v72, v64
	v_add_u32_e32 v108, v73, v64
	ds_read_b64_tr_b16 v[40:41], v104 offset:27648
	ds_read_b64_tr_b16 v[42:43], v104 offset:28224
	v_exp_f32_e32 v60, v118
	v_exp_f32_e32 v61, v119
	ds_read_b128 v[44:47], v109 offset:36864
	v_exp_f32_e32 v62, v120
	v_exp_f32_e32 v63, v121
	ds_read_b128 v[36:39], v108 offset:36864
	s_waitcnt lgkmcnt(1)
	v_mfma_f32_16x16x32_bf16 v[44:47], v[40:43], v[44:47], 0
	ds_read_b64_tr_b16 v[48:49], v104 offset:18432
	ds_read_b64_tr_b16 v[50:51], v104 offset:19008
	ds_read_b64_tr_b16 v[52:53], v104 offset:32256
	v_pk_mul_f32 v[30:31], v[30:31], v[62:63]
	v_pk_mul_f32 v[28:29], v[28:29], v[60:61]
	s_waitcnt lgkmcnt(3)
	v_mfma_f32_16x16x32_bf16 v[36:39], v[40:43], v[36:39], 0
	ds_read_b64_tr_b16 v[40:41], v106 offset:27648
	ds_read_b64_tr_b16 v[42:43], v106 offset:28224
	ds_read_b64_tr_b16 v[56:57], v107 offset:27648
	ds_read_b64_tr_b16 v[58:59], v107 offset:28224
	ds_read_b64_tr_b16 v[54:55], v104 offset:32832
	v_pk_mul_f32 v[34:35], v[34:35], v[62:63]
	v_pk_mul_f32 v[32:33], v[32:33], v[60:61]
	s_waitcnt lgkmcnt(3)
	v_mfma_f32_16x16x32_bf16 v[28:31], v[48:51], v[40:43], v[28:31]
	v_add_u32_e32 v113, v72, v74
	v_add_u32_e32 v112, v73, v74
	v_readlane_b32 s4, v255, 10
	s_waitcnt lgkmcnt(1)
	v_mfma_f32_16x16x32_bf16 v[40:43], v[48:51], v[56:59], v[32:35]
	s_nop 2
	ds_read_b128 v[32:35], v109 offset:36928
	ds_read_b64_tr_b16 v[48:49], v104 offset:23616
	ds_read_b128 v[56:59], v108 offset:36928
	s_and_b64 vcc, exec, s[34:35]
	s_waitcnt lgkmcnt(2)
	v_mfma_f32_16x16x32_bf16 v[60:63], v[52:55], v[32:35], v[44:47]
	s_nop 2
	ds_read_b64_tr_b16 v[46:47], v104 offset:23040
	ds_read_b64_tr_b16 v[32:33], v106 offset:32256
	s_waitcnt lgkmcnt(2)
	v_mfma_f32_16x16x32_bf16 v[36:39], v[52:55], v[56:59], v[36:39]
	ds_read_b64_tr_b16 v[34:35], v106 offset:32832
	ds_read_b64_tr_b16 v[50:51], v107 offset:32256
	ds_read_b64_tr_b16 v[52:53], v107 offset:32832
	ds_read_b128 v[54:57], v105 offset:46080
	s_waitcnt lgkmcnt(3)
	v_mfma_f32_16x16x32_bf16 v[32:35], v[46:49], v[32:35], v[28:31]
	s_waitcnt lgkmcnt(1)
	v_mfma_f32_16x16x32_bf16 v[28:31], v[46:49], v[50:53], v[40:43]
	s_nop 2
	ds_read_b128 v[40:43], v109 offset:9216
	ds_read_b128 v[44:47], v108 offset:9216
	ds_read_b128 v[48:51], v105 offset:46144
	s_waitcnt lgkmcnt(1)
	v_mfma_f32_16x16x32_bf16 v[36:39], v[54:57], v[44:47], v[36:39]
	ds_read_b128 v[44:47], v109 offset:9280
	v_mfma_f32_16x16x32_bf16 v[40:43], v[54:57], v[40:43], v[60:63]
	s_waitcnt lgkmcnt(0)
	v_mfma_f32_16x16x32_bf16 v[40:43], v[48:51], v[44:47], v[40:43]
	ds_read_b128 v[44:47], v108 offset:9280
	s_waitcnt lgkmcnt(0)
	v_mfma_f32_16x16x32_bf16 v[36:39], v[48:51], v[44:47], v[36:39]
	v_cvt_pk_bf16_f32 v44, v32, v33
	v_cvt_pk_bf16_f32 v45, v34, v35
	ds_write_b64 v113, v[44:45] offset:55296
	v_cvt_pk_bf16_f32 v44, v28, v29
	v_cvt_pk_bf16_f32 v45, v30, v31
	ds_write_b64 v112, v[44:45] offset:55296
	v_add_u32_e32 v44, s48, v75
	v_lshl_or_b32 v180, v44, 10, v76
	v_cvt_pk_bf16_f32 v40, v40, v41
	v_cvt_pk_bf16_f32 v41, v42, v43
	v_lshl_add_u64 v[42:43], v[180:181], 1, s[92:93]
	global_store_dwordx2 v[42:43], v[40:41], off nt
	v_add_u32_e32 v40, s48, v77
	v_lshl_or_b32 v180, v40, 10, v76
	v_cvt_pk_bf16_f32 v36, v36, v37
	v_cvt_pk_bf16_f32 v37, v38, v39
	v_lshl_add_u64 v[38:39], v[180:181], 1, s[92:93]
	global_store_dwordx2 v[38:39], v[36:37], off nt
	v_mov_b32_e32 v36, v68
	s_waitcnt lgkmcnt(0)
	s_barrier
	v_mov_b32_e32 v43, 0
	v_lshrrev_b32_e32 v37, 3, v36
	v_and_or_b32 v40, v37, 7, s70
	v_and_b32_e32 v41, 7, v36
	v_lshlrev_b32_e32 v36, 8, v40
	v_lshlrev_b32_e32 v37, 5, v41
	v_add3_u32 v36, s4, v36, v37
	ds_read_b128 v[44:47], v36
	ds_read_b128 v[36:39], v36 offset:16
	v_mul_lo_u32 v116, v40, s72
	v_lshlrev_b32_e32 v117, 4, v41
	v_lshlrev_b32_e32 v115, 3, v41
	v_add3_u32 v114, 0, v116, v117
	v_mov_b32_e32 v42, 0
	v_mov_b32_e32 v41, 0
	v_mov_b32_e32 v40, 0
	v_mov_b32_e32 v51, 0
	v_mov_b32_e32 v50, 0
	v_mov_b32_e32 v49, 0
	v_mov_b32_e32 v48, 0
	s_waitcnt vmcnt(7)
	ds_write_b128 v114, v[24:27] offset:27648
	s_cbranch_vccnz .LBB0_510
	v_lshl_add_u32 v40, v115, 2, s62
	ds_read_b128 v[48:51], v40
	ds_read_b128 v[40:43], v40 offset:16

.LBB0_548:
	v_mul_u32_u24_e32 v22, 0x90, v22
	v_add_u32_e32 v22, 0, v22
	s_lshl_b32 s4, s4, 2
	v_and_or_b32 v21, s4, -16, v21
	v_add_u32_e32 v69, v22, v79
	s_waitcnt lgkmcnt(0)
	s_barrier
	ds_read_b128 v[22:25], v69 offset:27648
	v_mul_lo_u32 v26, v21, s61
	v_add_u32_e32 v76, 0, v26
	v_add_u32_e32 v110, 0x1200, v76
	v_add_u32_e32 v70, v76, v79
	v_add_u32_e32 v71, v110, v79
	ds_read_b128 v[72:75], v70 offset:46080
	ds_read_b128 v[82:85], v71 offset:46080
	s_waitcnt lgkmcnt(1)
	v_mfma_f32_16x16x32_bf16 v[72:75], v[22:25], v[72:75], 0
	ds_read_b128 v[86:89], v69 offset:36864
	ds_read_b128 v[90:93], v70 offset:27648
	ds_read_b128 v[98:101], v69 offset:27712
	v_mul_f32_e32 v94, 0, v28
	s_waitcnt lgkmcnt(3)
	v_mfma_f32_16x16x32_bf16 v[22:25], v[22:25], v[82:85], 0
	ds_read_b128 v[82:85], v71 offset:27648
	v_mov_b32_e32 v95, v94
	v_mov_b32_e32 v96, v94
	v_mov_b32_e32 v97, v94
	v_or_b32_e32 v20, s12, v20
	v_lshlrev_b32_e32 v111, 1, v20
	s_waitcnt lgkmcnt(2)
	v_mfma_f32_16x16x32_bf16 v[90:93], v[86:89], v[90:93], v[94:97]
	s_and_b64 s[12:13], s[8:9], exec
	s_cselect_b32 s4, 0xc0, 63
	s_or_b32 s2, s4, s2
	s_waitcnt lgkmcnt(0)
	v_mfma_f32_16x16x32_bf16 v[82:85], v[86:89], v[82:85], v[94:97]
	ds_read_b128 v[86:89], v70 offset:46144
	s_nop 1
	ds_read_b128 v[94:97], v69 offset:36928
	ds_read_b128 v[102:105], v71 offset:46144
	s_and_b64 s[12:13], s[8:9], exec
	s_cselect_b32 s4, s92, 0x1b485000
	s_waitcnt lgkmcnt(2)
	v_mfma_f32_16x16x32_bf16 v[86:89], v[98:101], v[86:89], v[72:75]
	s_nop 2
	ds_read_b128 v[72:75], v70 offset:27712
	ds_read_b128 v[106:109], v71 offset:27712
	s_add_u32 s12, s78, s4
	s_addc_u32 s13, s79, 0
	s_waitcnt lgkmcnt(2)
	v_mfma_f32_16x16x32_bf16 v[98:101], v[98:101], v[102:105], v[22:25]
	ds_read_b128 v[102:105], v69 offset:55296
	v_mov_b32_e32 v31, v30
	s_andn2_b64 vcc, exec, s[6:7]
	s_waitcnt lgkmcnt(2)
	v_mfma_f32_16x16x32_bf16 v[24:27], v[94:97], v[72:75], v[90:93]
	v_mul_lo_u32 v72, v21, s19
	v_or_b32_e32 v73, s0, v20
	v_add_u32_e32 v75, v76, v111
	ds_read_b128 v[90:93], v70 offset:18432
	s_waitcnt lgkmcnt(2)
	v_mfma_f32_16x16x32_bf16 v[20:23], v[94:97], v[106:109], v[82:85]
	s_nop 2
	ds_read_b128 v[82:85], v69 offset:55360
	ds_read_b128 v[94:97], v70 offset:18496
	ds_read_b128 v[106:109], v71 offset:18432
	v_cvt_pk_bf16_f32 v58, v24, v25
	v_cvt_pk_bf16_f32 v59, v26, v27
	s_waitcnt lgkmcnt(3)
	v_mfma_f32_16x16x32_bf16 v[86:89], v[102:105], v[90:93], v[86:89]
	ds_read_b128 v[90:93], v71 offset:18496
	ds_write_b64 v75, v[58:59] offset:64512
	v_cvt_pk_bf16_f32 v58, v20, v21
	s_waitcnt lgkmcnt(2)
	v_mfma_f32_16x16x32_bf16 v[98:101], v[102:105], v[106:109], v[98:101]
	v_cvt_pk_bf16_f32 v59, v22, v23
	v_add_u32_e32 v76, v110, v111
	v_lshl_add_u32 v74, s19, 5, v72
	v_mfma_f32_16x16x32_bf16 v[86:89], v[82:85], v[94:97], v[86:89]
	ds_write_b64 v76, v[58:59] offset:64512
	s_waitcnt lgkmcnt(2)
	v_mfma_f32_16x16x32_bf16 v[82:85], v[82:85], v[90:93], v[98:101]
	v_add_u32_e32 v90, s5, v72
	v_lshl_or_b32 v180, v90, 10, v73
	s_nop 2
	v_cvt_pk_bf16_f32 v58, v86, v87
	v_cvt_pk_bf16_f32 v59, v88, v89
	v_lshl_add_u64 v[86:87], v[180:181], 1, s[12:13]
	global_store_dwordx2 v[86:87], v[58:59], off offset:512 nt
	v_add_u32_e32 v86, s5, v74
	v_lshl_or_b32 v180, v86, 10, v73
	v_cvt_pk_bf16_f32 v58, v82, v83
	v_cvt_pk_bf16_f32 v59, v84, v85
	v_lshl_add_u64 v[82:83], v[180:181], 1, s[12:13]
	global_store_dwordx2 v[82:83], v[58:59], off offset:512 nt
	s_waitcnt lgkmcnt(0)
	s_barrier
	s_waitcnt vmcnt(13)
	ds_write_b128 v62, v[12:15]
	s_waitcnt vmcnt(12)
	ds_write_b128 v62, v[16:19] offset:9216
	v_lshlrev_b32_e32 v16, 16, v12
	v_and_b32_e32 v17, 0xffff0000, v12
	v_pk_mul_f32 v[16:17], v[30:31], v[16:17]
	s_mov_b64 s[4:5], -1
	v_cvt_pk_bf16_f32 v12, v16, v17
	v_lshlrev_b32_e32 v16, 16, v13
	v_and_b32_e32 v17, 0xffff0000, v13
	v_pk_mul_f32 v[16:17], v[30:31], v[16:17]
	s_nop 0
	v_cvt_pk_bf16_f32 v13, v16, v17
	v_lshlrev_b32_e32 v16, 16, v14
	v_and_b32_e32 v17, 0xffff0000, v14
	v_pk_mul_f32 v[16:17], v[30:31], v[16:17]
	s_nop 0
	v_cvt_pk_bf16_f32 v14, v16, v17
	v_lshlrev_b32_e32 v16, 16, v15
	v_and_b32_e32 v17, 0xffff0000, v15
	v_pk_mul_f32 v[16:17], v[30:31], v[16:17]
	s_nop 0
	v_cvt_pk_bf16_f32 v15, v16, v17
	ds_write_b128 v62, v[12:15] offset:18432
	s_waitcnt vmcnt(11)
	v_and_b32_e32 v12, 0xffff, v42
	s_waitcnt vmcnt(10)
	v_lshl_or_b32 v14, v52, 16, v12
	s_waitcnt vmcnt(9)
	v_lshlrev_b32_e32 v13, 16, v56
	s_waitcnt vmcnt(8)
	v_lshlrev_b32_e32 v12, 16, v54
	v_pk_mul_f32 v[12:13], v[32:33], v[12:13]
	s_nop 0
	v_cvt_pk_bf16_f32 v15, v12, v13
	v_lshrrev_b32_e32 v12, 16, v42
	v_and_or_b32 v12, v52, s60, v12
	ds_write2_b32 v63, v14, v12 offset1:36
	v_and_b32_e32 v13, 0xffff0000, v56
	v_and_b32_e32 v12, 0xffff0000, v54
	v_pk_mul_f32 v[12:13], v[32:33], v[12:13]
	v_add_u32_e32 v42, s2, v67
	v_cvt_pk_bf16_f32 v12, v12, v13
	ds_write2_b32 v64, v15, v12 offset1:36
	v_and_b32_e32 v12, 0xffff, v43
	v_lshl_or_b32 v14, v53, 16, v12
	v_lshlrev_b32_e32 v13, 16, v57
	v_lshlrev_b32_e32 v12, 16, v55
	v_pk_mul_f32 v[12:13], v[32:33], v[12:13]
	v_mad_u32_u24 v42, v42, s63, v61
	v_cvt_pk_bf16_f32 v15, v12, v13
	v_lshrrev_b32_e32 v12, 16, v43
	v_and_or_b32 v12, v53, s60, v12
	ds_write2_b32 v63, v14, v12 offset0:72 offset1:108
	v_and_b32_e32 v13, 0xffff0000, v57
	v_and_b32_e32 v12, 0xffff0000, v55
	v_pk_mul_f32 v[12:13], v[32:33], v[12:13]
	v_ashrrev_i32_e32 v43, 31, v42
	v_cvt_pk_bf16_f32 v12, v12, v13
	ds_write2_b32 v64, v15, v12 offset0:72 offset1:108
	v_add_u32_e32 v12, s2, v60
	v_mul_u32_u24_e32 v12, 0xe00, v12
	v_or3_b32 v12, v12, v77, s0
	v_ashrrev_i32_e32 v13, 31, v12
	v_lshl_add_u64 v[42:43], v[42:43], 1, s[82:83]
	v_lshl_add_u64 v[16:17], v[12:13], 1, s[82:83]
	v_lshl_add_u64 v[52:53], s[10:11], 1, v[42:43]
	s_waitcnt lgkmcnt(0)
	s_barrier
	global_load_dwordx4 v[12:15], v[16:17], off offset:2560
	s_nop 0
	global_load_dwordx4 v[16:19], v[16:17], off offset:3072
	s_nop 0
	global_load_dwordx2 v[56:57], v[42:43], off offset:3584
	global_load_dwordx2 v[58:59], v[52:53], off offset:3584
	global_load_dwordx2 v[54:55], v[52:53], off offset:3072
	s_nop 0
	global_load_dwordx2 v[52:53], v[42:43], off offset:3072
	ds_read_b128 v[82:85], v65 offset:9216
	ds_read_b128 v[86:89], v66
	ds_read_b128 v[90:93], v65 offset:9280
	s_waitcnt lgkmcnt(1)
	v_mfma_f32_16x16x32_bf16 v[82:85], v[82:85], v[86:89], 0
	ds_read_b128 v[86:89], v66 offset:64
	s_waitcnt lgkmcnt(0)
	v_mfma_f32_16x16x32_bf16 v[82:85], v[90:93], v[86:89], v[82:85]
	s_nop 7
	v_pk_mul_f32 v[42:43], v[34:35], v[82:83]
	v_pk_mul_f32 v[82:83], v[38:39], v[84:85]
	v_cvt_pk_bf16_f32 v42, v42, v43
	v_cvt_pk_bf16_f32 v43, v82, v83
	ds_write_b64 v68, v[42:43] offset:46080
	s_cbranch_vccnz .LBB0_550
	s_lshl_b32 s6, s18, 5
	v_mul_u32_u24_e32 v82, 0x90, v81
	s_mov_b64 s[4:5], 0
	v_mov_b32_e32 v83, s6

.LBB0_552:
	s_waitcnt lgkmcnt(0)
	s_barrier
	ds_read_b128 v[84:87], v69 offset:27648
	ds_read_b128 v[88:91], v70 offset:46080
	ds_read_b128 v[92:95], v69 offset:36864
	ds_read_b128 v[96:99], v71 offset:46080
	s_waitcnt lgkmcnt(2)
	v_mfma_f32_16x16x32_bf16 v[88:91], v[84:87], v[88:91], 0
	ds_read_b128 v[100:103], v70 offset:27648
	ds_read_b128 v[104:107], v71 offset:27648
	v_mov_b32_e32 v42, v28
	v_mov_b32_e32 v43, v28
	s_waitcnt lgkmcnt(2)
	v_mfma_f32_16x16x32_bf16 v[84:87], v[84:87], v[96:99], 0
	ds_read_b128 v[96:99], v69 offset:27712
	v_mov_b32_e32 v29, v28
	v_pk_mul_f32 v[26:27], v[28:29], v[26:27]
	v_pk_mul_f32 v[24:25], v[42:43], v[24:25]
	v_pk_mul_f32 v[22:23], v[28:29], v[22:23]
	v_pk_mul_f32 v[20:21], v[42:43], v[20:21]
	s_waitcnt lgkmcnt(2)
	v_mfma_f32_16x16x32_bf16 v[24:27], v[92:95], v[100:103], v[24:27]
	v_add_u32_e32 v81, s17, v72
	v_lshl_or_b32 v180, v81, 10, v73
	v_add_u32_e32 v81, s17, v74
	s_waitcnt lgkmcnt(1)
	v_mfma_f32_16x16x32_bf16 v[20:23], v[92:95], v[104:107], v[20:23]
	ds_read_b128 v[92:95], v70 offset:46144
	ds_read_b128 v[100:103], v71 offset:46144
	s_lshl_b32 s1, s1, 12
	s_bitset1_b32 s1, 11
	s_waitcnt lgkmcnt(1)
	v_mfma_f32_16x16x32_bf16 v[88:91], v[96:99], v[92:95], v[88:91]
	ds_read_b128 v[92:95], v69 offset:36928
	s_and_b64 s[4:5], s[8:9], exec
	s_cselect_b32 s4, 0, 0xfff
	s_waitcnt lgkmcnt(1)
	v_mfma_f32_16x16x32_bf16 v[84:87], v[96:99], v[100:103], v[84:87]
	ds_read_b128 v[96:99], v70 offset:27712
	ds_read_b128 v[100:103], v71 offset:27712
	s_add_i32 s4, s1, s4
	s_andn2_b64 vcc, exec, s[14:15]
	s_waitcnt lgkmcnt(1)
	v_mfma_f32_16x16x32_bf16 v[24:27], v[92:95], v[96:99], v[24:27]
	ds_read_b128 v[96:99], v69 offset:64512
	s_waitcnt lgkmcnt(1)
	v_mfma_f32_16x16x32_bf16 v[20:23], v[92:95], v[100:103], v[20:23]
	ds_read_b128 v[92:95], v70 offset:18432
	ds_read_b128 v[100:103], v69 offset:64576
	ds_read_b128 v[104:107], v71 offset:18432
	ds_read_b128 v[108:111], v71 offset:18496
	s_waitcnt lgkmcnt(3)
	v_mfma_f32_16x16x32_bf16 v[88:91], v[96:99], v[92:95], v[88:91]
	ds_read_b128 v[92:95], v70 offset:18496
	s_waitcnt lgkmcnt(2)
	v_mfma_f32_16x16x32_bf16 v[84:87], v[96:99], v[104:107], v[84:87]
	v_cvt_pk_bf16_f32 v96, v24, v25
	v_cvt_pk_bf16_f32 v97, v26, v27
	ds_write_b64 v75, v[96:97] offset:55296
	s_waitcnt lgkmcnt(1)
	v_mfma_f32_16x16x32_bf16 v[88:91], v[100:103], v[92:95], v[88:91]
	v_cvt_pk_bf16_f32 v92, v20, v21
	v_cvt_pk_bf16_f32 v93, v22, v23
	ds_write_b64 v76, v[92:93] offset:55296
	v_mfma_f32_16x16x32_bf16 v[84:87], v[100:103], v[108:111], v[84:87]
	s_nop 3
	v_cvt_pk_bf16_f32 v88, v88, v89
	v_cvt_pk_bf16_f32 v89, v90, v91
	v_lshl_add_u64 v[90:91], v[180:181], 1, s[12:13]
	v_lshl_or_b32 v180, v81, 10, v73
	v_cvt_pk_bf16_f32 v84, v84, v85
	v_cvt_pk_bf16_f32 v85, v86, v87
	v_lshl_add_u64 v[86:87], v[180:181], 1, s[12:13]
	global_store_dwordx2 v[90:91], v[88:89], off offset:512 nt
	global_store_dwordx2 v[86:87], v[84:85], off offset:512 nt
	s_waitcnt lgkmcnt(0)
	s_barrier
	s_waitcnt vmcnt(15)
	ds_write_b128 v62, v[4:7]
	s_waitcnt vmcnt(14)
	ds_write_b128 v62, v[8:11] offset:9216
	v_lshlrev_b32_e32 v8, 16, v4
	v_and_b32_e32 v9, 0xffff0000, v4
	v_pk_mul_f32 v[8:9], v[30:31], v[8:9]
	s_nop 0
	v_cvt_pk_bf16_f32 v4, v8, v9
	v_lshlrev_b32_e32 v8, 16, v5
	v_and_b32_e32 v9, 0xffff0000, v5
	v_pk_mul_f32 v[8:9], v[30:31], v[8:9]
	s_nop 0
	v_cvt_pk_bf16_f32 v5, v8, v9
	v_lshlrev_b32_e32 v8, 16, v6
	v_and_b32_e32 v9, 0xffff0000, v6
	v_pk_mul_f32 v[8:9], v[30:31], v[8:9]
	s_nop 0
	v_cvt_pk_bf16_f32 v6, v8, v9
	v_lshlrev_b32_e32 v8, 16, v7
	v_and_b32_e32 v9, 0xffff0000, v7
	v_pk_mul_f32 v[8:9], v[30:31], v[8:9]
	s_nop 0
	v_cvt_pk_bf16_f32 v7, v8, v9
	ds_write_b128 v62, v[4:7] offset:18432
	s_waitcnt vmcnt(13)
	v_and_b32_e32 v4, 0xffff, v44
	s_waitcnt vmcnt(12)
	v_lshl_or_b32 v6, v46, 16, v4
	s_waitcnt vmcnt(11)
	v_lshlrev_b32_e32 v5, 16, v50
	s_waitcnt vmcnt(10)
	v_lshlrev_b32_e32 v4, 16, v48
	v_pk_mul_f32 v[4:5], v[32:33], v[4:5]
	s_nop 0
	v_cvt_pk_bf16_f32 v7, v4, v5
	v_lshrrev_b32_e32 v4, 16, v44
	v_and_or_b32 v4, v46, s60, v4
	ds_write2_b32 v63, v6, v4 offset1:36
	v_and_b32_e32 v5, 0xffff0000, v50
	v_and_b32_e32 v4, 0xffff0000, v48
	v_pk_mul_f32 v[4:5], v[32:33], v[4:5]
	v_add_u32_e32 v44, s4, v67
	v_cvt_pk_bf16_f32 v4, v4, v5
	ds_write2_b32 v64, v7, v4 offset1:36
	v_and_b32_e32 v4, 0xffff, v45
	v_lshl_or_b32 v6, v47, 16, v4
	v_lshlrev_b32_e32 v5, 16, v51
	v_lshlrev_b32_e32 v4, 16, v49
	v_pk_mul_f32 v[4:5], v[32:33], v[4:5]
	v_mad_u32_u24 v44, v44, s63, v61
	v_cvt_pk_bf16_f32 v7, v4, v5
	v_lshrrev_b32_e32 v4, 16, v45
	v_and_or_b32 v4, v47, s60, v4
	ds_write2_b32 v63, v6, v4 offset0:72 offset1:108
	v_and_b32_e32 v5, 0xffff0000, v51
	v_and_b32_e32 v4, 0xffff0000, v49
	v_pk_mul_f32 v[4:5], v[32:33], v[4:5]
	v_ashrrev_i32_e32 v45, 31, v44
	v_cvt_pk_bf16_f32 v4, v4, v5
	ds_write2_b32 v64, v7, v4 offset0:72 offset1:108
	v_add_u32_e32 v4, s4, v60
	v_mul_u32_u24_e32 v4, 0xe00, v4
	v_or3_b32 v4, v4, v77, s0
	v_ashrrev_i32_e32 v5, 31, v4
	v_lshl_add_u64 v[50:51], v[44:45], 1, s[82:83]
	v_lshl_add_u64 v[8:9], v[4:5], 1, s[82:83]
	v_lshl_add_u64 v[48:49], s[10:11], 1, v[50:51]
	s_waitcnt lgkmcnt(0)
	s_barrier
	global_load_dwordx4 v[4:7], v[8:9], off offset:2560
	s_nop 0
	global_load_dwordx4 v[8:11], v[8:9], off offset:3072
	s_nop 0
	global_load_dwordx2 v[44:45], v[50:51], off offset:3584
	global_load_dwordx2 v[46:47], v[48:49], off offset:3584
	s_nop 0
	global_load_dwordx2 v[48:49], v[48:49], off offset:3072
	s_nop 0
	global_load_dwordx2 v[50:51], v[50:51], off offset:3072
	ds_read_b128 v[84:87], v65 offset:9216
	ds_read_b128 v[88:91], v65 offset:9280
	ds_read_b128 v[92:95], v66
	ds_read_b128 v[96:99], v66 offset:64
	s_waitcnt lgkmcnt(1)
	v_mfma_f32_16x16x32_bf16 v[84:87], v[84:87], v[92:95], 0
	v_add_u32_e32 v92, 0, v80
	v_add_u32_e32 v93, 0, v82
	v_add_u32_e32 v82, v78, v82
	s_waitcnt lgkmcnt(0)
	v_mfma_f32_16x16x32_bf16 v[84:87], v[88:91], v[96:99], v[84:87]
	v_cndmask_b32_e64 v78, 0, 1, s[14:15]
	v_cmp_ne_u32_e64 s[6:7], 1, v78
	v_add_u32_e32 v78, v92, v79
	v_add_u32_e32 v79, v93, v79
	s_nop 3
	v_pk_mul_f32 v[80:81], v[34:35], v[84:85]
	v_pk_mul_f32 v[84:85], v[38:39], v[86:87]
	v_cvt_pk_bf16_f32 v80, v80, v81
	v_cvt_pk_bf16_f32 v81, v84, v85
	ds_write_b64 v68, v[80:81] offset:46080
	v_add_u32_e32 v80, v82, v83
	s_cbranch_vccnz .LBB0_554
	ds_read_b128 v[82:85], v78 offset:9216
	ds_read_b128 v[86:89], v79
	ds_read_b128 v[90:93], v78 offset:9280
	s_waitcnt lgkmcnt(1)
	v_mfma_f32_16x16x32_bf16 v[82:85], v[82:85], v[86:89], 0
	ds_read_b128 v[86:89], v79 offset:64
	s_waitcnt lgkmcnt(0)
	v_mfma_f32_16x16x32_bf16 v[82:85], v[90:93], v[86:89], v[82:85]
	s_nop 7
	v_pk_mul_f32 v[82:83], v[36:37], v[82:83]
	v_pk_mul_f32 v[84:85], v[40:41], v[84:85]
	v_cvt_pk_bf16_f32 v82, v82, v83
	v_cvt_pk_bf16_f32 v83, v84, v85
	ds_write_b64 v80, v[82:83] offset:46080
.LBB0_554:
	s_waitcnt lgkmcnt(0)
	s_barrier
	ds_read_b128 v[82:85], v69 offset:27648
	ds_read_b128 v[86:89], v70 offset:46080
	ds_read_b128 v[90:93], v69 offset:36864
	ds_read_b128 v[94:97], v71 offset:46080
	ds_read_b128 v[98:101], v70 offset:27648
	v_pk_mul_f32 v[26:27], v[28:29], v[26:27]
	v_pk_mul_f32 v[24:25], v[42:43], v[24:25]
	s_waitcnt lgkmcnt(3)
	v_mfma_f32_16x16x32_bf16 v[86:89], v[82:85], v[86:89], 0
	v_mul_f32_e64 v22, v28, v22
	v_mul_f32_e64 v23, v29, v23
	v_pk_mul_f32 v[20:21], v[42:43], v[20:21]
	v_add_u32_e32 v29, s16, v72
	s_waitcnt lgkmcnt(1)
	v_mfma_f32_16x16x32_bf16 v[82:85], v[82:85], v[94:97], 0
	ds_read_b128 v[94:97], v71 offset:27648
	v_lshl_or_b32 v180, v29, 10, v73
	v_add_u32_e32 v29, s16, v74
	s_waitcnt lgkmcnt(1)
	v_mfma_f32_16x16x32_bf16 v[24:27], v[90:93], v[98:101], v[24:27]
	ds_read_b128 v[98:101], v69 offset:27712
	s_and_b64 s[4:5], s[8:9], exec
	s_cselect_b32 s4, 64, 0xfbf
	s_waitcnt lgkmcnt(1)
	v_mfma_f32_16x16x32_bf16 v[20:23], v[90:93], v[94:97], v[20:23]
	ds_read_b128 v[90:93], v70 offset:46144
	ds_read_b128 v[94:97], v71 offset:46144
	s_add_i32 s4, s1, s4
	s_and_b64 vcc, exec, s[6:7]
	s_waitcnt lgkmcnt(1)
	v_mfma_f32_16x16x32_bf16 v[86:89], v[98:101], v[90:93], v[86:89]
	ds_read_b128 v[90:93], v69 offset:36928
	s_waitcnt lgkmcnt(1)
	v_mfma_f32_16x16x32_bf16 v[82:85], v[98:101], v[94:97], v[82:85]
	ds_read_b128 v[94:97], v70 offset:27712
	ds_read_b128 v[98:101], v71 offset:27712
	ds_read_b128 v[102:105], v69 offset:55296
	s_waitcnt lgkmcnt(2)
	v_mfma_f32_16x16x32_bf16 v[24:27], v[90:93], v[94:97], v[24:27]
	ds_read_b128 v[94:97], v69 offset:55360
	ds_read_b128 v[106:109], v70 offset:18432
	ds_read_b128 v[110:113], v70 offset:18496
	s_nop 4
	v_cvt_pk_bf16_f32 v114, v24, v25
	s_waitcnt lgkmcnt(4)
	v_mfma_f32_16x16x32_bf16 v[20:23], v[90:93], v[98:101], v[20:23]
	ds_read_b128 v[90:93], v71 offset:18432
	ds_read_b128 v[98:101], v71 offset:18496
	v_cvt_pk_bf16_f32 v115, v26, v27
	ds_write_b64 v75, v[114:115] offset:64512
	s_waitcnt lgkmcnt(4)
	v_mfma_f32_16x16x32_bf16 v[86:89], v[102:105], v[106:109], v[86:89]
	s_nop 1
	v_cvt_pk_bf16_f32 v106, v20, v21
	v_cvt_pk_bf16_f32 v107, v22, v23
	ds_write_b64 v76, v[106:107] offset:64512
	s_waitcnt lgkmcnt(3)
	v_mfma_f32_16x16x32_bf16 v[82:85], v[102:105], v[90:93], v[82:85]
	v_mfma_f32_16x16x32_bf16 v[86:89], v[94:97], v[110:113], v[86:89]
	s_waitcnt lgkmcnt(2)
	v_mfma_f32_16x16x32_bf16 v[82:85], v[94:97], v[98:101], v[82:85]
	s_nop 5
	v_cvt_pk_bf16_f32 v86, v86, v87
	v_cvt_pk_bf16_f32 v87, v88, v89
	v_lshl_add_u64 v[88:89], v[180:181], 1, s[12:13]
	v_lshl_or_b32 v180, v29, 10, v73
	v_cvt_pk_bf16_f32 v82, v82, v83
	v_cvt_pk_bf16_f32 v83, v84, v85
	v_lshl_add_u64 v[84:85], v[180:181], 1, s[12:13]
	global_store_dwordx2 v[88:89], v[86:87], off offset:512 nt
	global_store_dwordx2 v[84:85], v[82:83], off offset:512 nt
	s_waitcnt lgkmcnt(0)
	s_barrier
	s_waitcnt vmcnt(15)
	ds_write_b128 v62, v[12:15]
	s_waitcnt vmcnt(14)
	ds_write_b128 v62, v[16:19] offset:9216
	v_lshlrev_b32_e32 v16, 16, v12
	v_and_b32_e32 v17, 0xffff0000, v12
	v_pk_mul_f32 v[16:17], v[30:31], v[16:17]
	v_add_u32_e32 v29, s4, v67
	v_cvt_pk_bf16_f32 v12, v16, v17
	v_lshlrev_b32_e32 v16, 16, v13
	v_and_b32_e32 v17, 0xffff0000, v13
	v_pk_mul_f32 v[16:17], v[30:31], v[16:17]
	s_nop 0
	v_cvt_pk_bf16_f32 v13, v16, v17
	v_lshlrev_b32_e32 v16, 16, v14
	v_and_b32_e32 v17, 0xffff0000, v14
	v_pk_mul_f32 v[16:17], v[30:31], v[16:17]
	s_nop 0
	v_cvt_pk_bf16_f32 v14, v16, v17
	v_lshlrev_b32_e32 v16, 16, v15
	v_and_b32_e32 v17, 0xffff0000, v15
	v_pk_mul_f32 v[16:17], v[30:31], v[16:17]
	s_nop 0
	v_cvt_pk_bf16_f32 v15, v16, v17
	ds_write_b128 v62, v[12:15] offset:18432
	s_waitcnt vmcnt(13)
	v_and_b32_e32 v12, 0xffff, v56
	s_waitcnt vmcnt(12)
	v_lshl_or_b32 v14, v58, 16, v12
	s_waitcnt vmcnt(11)
	v_lshlrev_b32_e32 v13, 16, v54
	s_waitcnt vmcnt(10)
	v_lshlrev_b32_e32 v12, 16, v52
	v_pk_mul_f32 v[12:13], v[32:33], v[12:13]
	s_nop 0
	v_cvt_pk_bf16_f32 v15, v12, v13
	v_lshrrev_b32_e32 v12, 16, v56
	v_and_or_b32 v12, v58, s60, v12
	ds_write2_b32 v63, v14, v12 offset1:36
	v_and_b32_e32 v13, 0xffff0000, v54
	v_and_b32_e32 v12, 0xffff0000, v52
	v_pk_mul_f32 v[12:13], v[32:33], v[12:13]
	v_mad_u32_u24 v52, v29, s63, v61
	v_cvt_pk_bf16_f32 v12, v12, v13
	ds_write2_b32 v64, v15, v12 offset1:36
	v_and_b32_e32 v12, 0xffff, v57
	v_lshl_or_b32 v14, v59, 16, v12
	v_lshlrev_b32_e32 v13, 16, v55
	v_lshlrev_b32_e32 v12, 16, v53
	v_pk_mul_f32 v[12:13], v[32:33], v[12:13]
	s_nop 0
	v_cvt_pk_bf16_f32 v15, v12, v13
	v_lshrrev_b32_e32 v12, 16, v57
	v_and_or_b32 v12, v59, s60, v12
	ds_write2_b32 v63, v14, v12 offset0:72 offset1:108
	v_and_b32_e32 v13, 0xffff0000, v55
	v_and_b32_e32 v12, 0xffff0000, v53
	v_pk_mul_f32 v[12:13], v[32:33], v[12:13]
	v_ashrrev_i32_e32 v53, 31, v52
	v_cvt_pk_bf16_f32 v12, v12, v13
	ds_write2_b32 v64, v15, v12 offset0:72 offset1:108
	v_add_u32_e32 v12, s4, v60
	v_mul_u32_u24_e32 v12, 0xe00, v12
	v_or3_b32 v12, v12, v77, s0
	v_ashrrev_i32_e32 v13, 31, v12
	v_lshl_add_u64 v[58:59], v[52:53], 1, s[82:83]
	v_lshl_add_u64 v[16:17], v[12:13], 1, s[82:83]
	v_lshl_add_u64 v[56:57], s[10:11], 1, v[58:59]
	s_waitcnt lgkmcnt(0)
	s_barrier
	global_load_dwordx4 v[12:15], v[16:17], off offset:2560
	s_nop 0
	global_load_dwordx4 v[16:19], v[16:17], off offset:3072
	s_nop 0
	global_load_dwordx2 v[52:53], v[58:59], off offset:3584
	global_load_dwordx2 v[54:55], v[56:57], off offset:3584
	s_nop 0
	global_load_dwordx2 v[56:57], v[56:57], off offset:3072
	s_nop 0
	global_load_dwordx2 v[58:59], v[58:59], off offset:3072
	ds_read_b128 v[82:85], v65 offset:9216
	ds_read_b128 v[86:89], v66
	ds_read_b128 v[90:93], v65 offset:9280
	s_waitcnt lgkmcnt(1)
	v_mfma_f32_16x16x32_bf16 v[82:85], v[82:85], v[86:89], 0
	ds_read_b128 v[86:89], v66 offset:64
	s_waitcnt lgkmcnt(0)
	v_mfma_f32_16x16x32_bf16 v[82:85], v[90:93], v[86:89], v[82:85]
	s_nop 7
	v_pk_mul_f32 v[82:83], v[34:35], v[82:83]
	v_pk_mul_f32 v[84:85], v[38:39], v[84:85]
	v_cvt_pk_bf16_f32 v82, v82, v83
	v_cvt_pk_bf16_f32 v83, v84, v85
	ds_write_b64 v68, v[82:83] offset:46080
	s_cbranch_vccnz .LBB0_556
	ds_read_b128 v[82:85], v78 offset:9216
	ds_read_b128 v[86:89], v79
	ds_read_b128 v[90:93], v78 offset:9280
	s_waitcnt lgkmcnt(1)
	v_mfma_f32_16x16x32_bf16 v[82:85], v[82:85], v[86:89], 0
	ds_read_b128 v[86:89], v79 offset:64
	s_waitcnt lgkmcnt(0)
	v_mfma_f32_16x16x32_bf16 v[82:85], v[90:93], v[86:89], v[82:85]
	s_nop 7
	v_pk_mul_f32 v[82:83], v[36:37], v[82:83]
	v_pk_mul_f32 v[84:85], v[40:41], v[84:85]
	v_cvt_pk_bf16_f32 v82, v82, v83
	v_cvt_pk_bf16_f32 v83, v84, v85
	ds_write_b64 v80, v[82:83] offset:46080
.LBB0_556:
	s_waitcnt lgkmcnt(0)
	s_barrier
	ds_read_b128 v[82:85], v69 offset:27648
	ds_read_b128 v[86:89], v70 offset:46080
	ds_read_b128 v[90:93], v69 offset:36864
	ds_read_b128 v[94:97], v71 offset:46080
	ds_read_b128 v[98:101], v70 offset:27648
	ds_read_b128 v[102:105], v71 offset:27648
	s_waitcnt lgkmcnt(4)
	v_mfma_f32_16x16x32_bf16 v[86:89], v[82:85], v[86:89], 0
	v_mov_b32_e32 v29, v28
	v_pk_mul_f32 v[26:27], v[28:29], v[26:27]
	v_pk_mul_f32 v[24:25], v[42:43], v[24:25]
	s_waitcnt lgkmcnt(2)
	v_mfma_f32_16x16x32_bf16 v[82:85], v[82:85], v[94:97], 0
	ds_read_b128 v[94:97], v69 offset:27712
	v_pk_mul_f32 v[22:23], v[28:29], v[22:23]
	v_pk_mul_f32 v[20:21], v[42:43], v[20:21]
	s_waitcnt lgkmcnt(2)
	v_mfma_f32_16x16x32_bf16 v[24:27], v[90:93], v[98:101], v[24:27]
	v_add_u32_e32 v29, s2, v72
	v_lshl_or_b32 v180, v29, 10, v73
	v_add_u32_e32 v29, s2, v74
	s_waitcnt lgkmcnt(1)
	v_mfma_f32_16x16x32_bf16 v[20:23], v[90:93], v[102:105], v[20:23]
	ds_read_b128 v[90:93], v70 offset:46144
	ds_read_b128 v[98:101], v71 offset:46144
	v_or_b32_e32 v77, s0, v77
	s_mov_b32 s0, 4
	s_waitcnt lgkmcnt(1)
	v_mfma_f32_16x16x32_bf16 v[86:89], v[94:97], v[90:93], v[86:89]
	ds_read_b128 v[90:93], v69 offset:36928
	s_movk_i32 s2, 0xfff
	s_movk_i32 s4, 0x80
	s_waitcnt lgkmcnt(1)
	v_mfma_f32_16x16x32_bf16 v[82:85], v[94:97], v[98:101], v[82:85]
	ds_read_b128 v[94:97], v70 offset:27712
	ds_read_b128 v[98:101], v71 offset:27712
	s_waitcnt lgkmcnt(1)
	v_mfma_f32_16x16x32_bf16 v[24:27], v[90:93], v[94:97], v[24:27]
	ds_read_b128 v[94:97], v69 offset:64512
	ds_read_b128 v[102:105], v69 offset:64576
	ds_read_b128 v[106:109], v70 offset:18432
	s_waitcnt lgkmcnt(3)
	v_mfma_f32_16x16x32_bf16 v[20:23], v[90:93], v[98:101], v[20:23]
	ds_read_b128 v[90:93], v70 offset:18496
	ds_read_b128 v[98:101], v71 offset:18432
	ds_read_b128 v[110:113], v71 offset:18496
	s_waitcnt lgkmcnt(3)
	v_mfma_f32_16x16x32_bf16 v[86:89], v[94:97], v[106:109], v[86:89]
	v_cvt_pk_bf16_f32 v106, v24, v25
	v_cvt_pk_bf16_f32 v107, v26, v27
	ds_write_b64 v75, v[106:107] offset:55296
	s_waitcnt lgkmcnt(2)
	v_mfma_f32_16x16x32_bf16 v[82:85], v[94:97], v[98:101], v[82:85]
	v_cvt_pk_bf16_f32 v94, v20, v21
	v_cvt_pk_bf16_f32 v95, v22, v23
	ds_write_b64 v76, v[94:95] offset:55296
	v_mfma_f32_16x16x32_bf16 v[86:89], v[102:105], v[90:93], v[86:89]
	s_waitcnt lgkmcnt(2)
	v_mfma_f32_16x16x32_bf16 v[82:85], v[102:105], v[110:113], v[82:85]
	s_nop 5
	v_cvt_pk_bf16_f32 v86, v86, v87
	v_cvt_pk_bf16_f32 v87, v88, v89
	v_lshl_add_u64 v[88:89], v[180:181], 1, s[12:13]
	v_lshl_or_b32 v180, v29, 10, v73
	v_cvt_pk_bf16_f32 v82, v82, v83
	v_cvt_pk_bf16_f32 v83, v84, v85
	v_lshl_add_u64 v[84:85], v[180:181], 1, s[12:13]
	global_store_dwordx2 v[88:89], v[86:87], off offset:512 nt
	global_store_dwordx2 v[84:85], v[82:83], off offset:512 nt
	s_waitcnt lgkmcnt(0)
	s_barrier
	s_branch .LBB0_558
.LBB0_557:
	s_waitcnt lgkmcnt(0)
	s_barrier
	ds_read_b128 v[82:85], v69 offset:27648
	ds_read_b128 v[86:89], v70 offset:46080
	ds_read_b128 v[90:93], v69 offset:36864
	ds_read_b128 v[94:97], v71 offset:46080
	ds_read_b128 v[98:101], v70 offset:27648
	ds_read_b128 v[102:105], v71 offset:27648
	s_waitcnt lgkmcnt(4)
	v_mfma_f32_16x16x32_bf16 v[86:89], v[82:85], v[86:89], 0
	v_mov_b32_e32 v29, v28
	v_pk_mul_f32 v[26:27], v[28:29], v[26:27]
	v_pk_mul_f32 v[24:25], v[42:43], v[24:25]
	s_waitcnt lgkmcnt(2)
	v_mfma_f32_16x16x32_bf16 v[82:85], v[82:85], v[94:97], 0
	ds_read_b128 v[94:97], v69 offset:27712
	v_pk_mul_f32 v[22:23], v[28:29], v[22:23]
	v_pk_mul_f32 v[20:21], v[42:43], v[20:21]
	s_waitcnt lgkmcnt(2)
	v_mfma_f32_16x16x32_bf16 v[24:27], v[90:93], v[98:101], v[24:27]
	s_and_b64 s[16:17], s[8:9], exec
	s_cselect_b32 s5, s4, s2
	s_add_i32 s5, s5, s1
	s_waitcnt lgkmcnt(1)
	v_mfma_f32_16x16x32_bf16 v[20:23], v[90:93], v[102:105], v[20:23]
	ds_read_b128 v[90:93], v70 offset:46144
	ds_read_b128 v[98:101], v71 offset:46144
	s_sub_i32 s5, s5, 64
	v_add_u32_e32 v29, s5, v72
	s_waitcnt lgkmcnt(1)
	v_mfma_f32_16x16x32_bf16 v[86:89], v[94:97], v[90:93], v[86:89]
	ds_read_b128 v[90:93], v69 offset:36928
	v_lshl_or_b32 v180, v29, 10, v73
	v_add_u32_e32 v29, s5, v74
	s_waitcnt lgkmcnt(1)
	v_mfma_f32_16x16x32_bf16 v[82:85], v[94:97], v[98:101], v[82:85]
	ds_read_b128 v[94:97], v70 offset:27712
	ds_read_b128 v[98:101], v71 offset:27712
	ds_read_b128 v[102:105], v70 offset:18432
	s_add_i32 s0, s0, 2
	s_waitcnt lgkmcnt(2)
	v_mfma_f32_16x16x32_bf16 v[24:27], v[90:93], v[94:97], v[24:27]
	ds_read_b128 v[94:97], v69 offset:64512
	s_addk_i32 s2, 0xff80
	s_addk_i32 s4, 0x80
	s_waitcnt lgkmcnt(2)
	v_mfma_f32_16x16x32_bf16 v[20:23], v[90:93], v[98:101], v[20:23]
	ds_read_b128 v[90:93], v69 offset:64576
	ds_read_b128 v[98:101], v70 offset:18496
	ds_read_b128 v[106:109], v71 offset:18432
	s_and_b64 vcc, exec, s[14:15]
	s_waitcnt lgkmcnt(3)
	v_mfma_f32_16x16x32_bf16 v[86:89], v[94:97], v[102:105], v[86:89]
	ds_read_b128 v[102:105], v71 offset:18496
	s_waitcnt lgkmcnt(1)
	v_mfma_f32_16x16x32_bf16 v[82:85], v[94:97], v[106:109], v[82:85]
	v_cvt_pk_bf16_f32 v94, v24, v25
	v_cvt_pk_bf16_f32 v95, v26, v27
	ds_write_b64 v75, v[94:95] offset:55296
	v_mfma_f32_16x16x32_bf16 v[86:89], v[90:93], v[98:101], v[86:89]
	v_cvt_pk_bf16_f32 v94, v20, v21
	v_cvt_pk_bf16_f32 v95, v22, v23
	ds_write_b64 v76, v[94:95] offset:55296
	s_waitcnt lgkmcnt(2)
	v_mfma_f32_16x16x32_bf16 v[82:85], v[90:93], v[102:105], v[82:85]
	s_nop 2
	v_cvt_pk_bf16_f32 v86, v86, v87
	v_cvt_pk_bf16_f32 v87, v88, v89
	v_lshl_add_u64 v[88:89], v[180:181], 1, s[12:13]
	v_lshl_or_b32 v180, v29, 10, v73
	s_nop 0
	v_cvt_pk_bf16_f32 v82, v82, v83
	v_cvt_pk_bf16_f32 v83, v84, v85
	v_lshl_add_u64 v[84:85], v[180:181], 1, s[12:13]
	global_store_dwordx2 v[88:89], v[86:87], off offset:512 nt
	global_store_dwordx2 v[84:85], v[82:83], off offset:512 nt
	s_waitcnt lgkmcnt(0)
	s_barrier
	s_cbranch_vccnz .LBB0_342

.LBB0_562:
	s_waitcnt lgkmcnt(0)
	s_barrier
	ds_read_b128 v[82:85], v69 offset:27648
	ds_read_b128 v[86:89], v70 offset:46080
	ds_read_b128 v[90:93], v69 offset:36864
	ds_read_b128 v[94:97], v71 offset:46080
	ds_read_b128 v[98:101], v70 offset:27648
	ds_read_b128 v[102:105], v71 offset:27648
	s_waitcnt lgkmcnt(4)
	v_mfma_f32_16x16x32_bf16 v[86:89], v[82:85], v[86:89], 0
	v_mov_b32_e32 v29, v28
	v_pk_mul_f32 v[26:27], v[28:29], v[26:27]
	v_pk_mul_f32 v[24:25], v[42:43], v[24:25]
	s_waitcnt lgkmcnt(2)
	v_mfma_f32_16x16x32_bf16 v[82:85], v[82:85], v[94:97], 0
	ds_read_b128 v[94:97], v69 offset:27712
	v_pk_mul_f32 v[22:23], v[28:29], v[22:23]
	v_pk_mul_f32 v[20:21], v[42:43], v[20:21]
	s_waitcnt lgkmcnt(2)
	v_mfma_f32_16x16x32_bf16 v[24:27], v[90:93], v[98:101], v[24:27]
	s_add_i32 s5, s4, 0xffffff80
	s_and_b64 s[18:19], s[8:9], exec
	s_cselect_b32 s5, s5, s2
	s_waitcnt lgkmcnt(1)
	v_mfma_f32_16x16x32_bf16 v[20:23], v[90:93], v[102:105], v[20:23]
	ds_read_b128 v[90:93], v70 offset:46144
	ds_read_b128 v[98:101], v71 offset:46144
	s_add_i32 s5, s5, s1
	v_add_u32_e32 v29, s5, v72
	s_waitcnt lgkmcnt(1)
	v_mfma_f32_16x16x32_bf16 v[86:89], v[94:97], v[90:93], v[86:89]
	ds_read_b128 v[90:93], v69 offset:36928
	v_lshl_or_b32 v180, v29, 10, v73
	v_add_u32_e32 v29, s5, v74
	s_waitcnt lgkmcnt(1)
	v_mfma_f32_16x16x32_bf16 v[82:85], v[94:97], v[98:101], v[82:85]
	ds_read_b128 v[94:97], v70 offset:27712
	ds_read_b128 v[98:101], v71 offset:27712
	ds_read_b128 v[102:105], v70 offset:18432
	s_mov_b32 s5, 0xffff
	s_waitcnt lgkmcnt(2)
	v_mfma_f32_16x16x32_bf16 v[24:27], v[90:93], v[94:97], v[24:27]
	ds_read_b128 v[94:97], v69 offset:55296
	s_andn2_b64 vcc, exec, s[16:17]
	s_waitcnt lgkmcnt(2)
	v_mfma_f32_16x16x32_bf16 v[20:23], v[90:93], v[98:101], v[20:23]
	ds_read_b128 v[90:93], v69 offset:55360
	ds_read_b128 v[98:101], v70 offset:18496
	ds_read_b128 v[106:109], v71 offset:18432
	s_waitcnt lgkmcnt(3)
	v_mfma_f32_16x16x32_bf16 v[86:89], v[94:97], v[102:105], v[86:89]
	ds_read_b128 v[102:105], v71 offset:18496
	s_waitcnt lgkmcnt(1)
	v_mfma_f32_16x16x32_bf16 v[82:85], v[94:97], v[106:109], v[82:85]
	v_cvt_pk_bf16_f32 v94, v24, v25
	v_cvt_pk_bf16_f32 v95, v26, v27
	ds_write_b64 v75, v[94:95] offset:64512
	v_mfma_f32_16x16x32_bf16 v[86:89], v[90:93], v[98:101], v[86:89]
	v_cvt_pk_bf16_f32 v94, v20, v21
	v_cvt_pk_bf16_f32 v95, v22, v23
	ds_write_b64 v76, v[94:95] offset:64512
	s_waitcnt lgkmcnt(2)
	v_mfma_f32_16x16x32_bf16 v[82:85], v[90:93], v[102:105], v[82:85]
	s_nop 2
	v_cvt_pk_bf16_f32 v86, v86, v87
	v_cvt_pk_bf16_f32 v87, v88, v89
	v_lshl_add_u64 v[88:89], v[180:181], 1, s[12:13]
	v_lshl_or_b32 v180, v29, 10, v73
	s_nop 0
	v_cvt_pk_bf16_f32 v82, v82, v83
	v_cvt_pk_bf16_f32 v83, v84, v85
	v_lshl_add_u64 v[84:85], v[180:181], 1, s[12:13]
	global_store_dwordx2 v[88:89], v[86:87], off offset:512 nt
	global_store_dwordx2 v[84:85], v[82:83], off offset:512 nt
	s_waitcnt vmcnt(9)
	v_lshlrev_b32_e32 v82, 16, v12
	v_and_b32_e32 v83, 0xffff0000, v12
	v_lshlrev_b32_e32 v84, 16, v13
	v_and_b32_e32 v85, 0xffff0000, v13
	v_pk_mul_f32 v[82:83], v[30:31], v[82:83]
	v_pk_mul_f32 v[84:85], v[30:31], v[84:85]
	v_cvt_pk_bf16_f32 v82, v82, v83
	v_cvt_pk_bf16_f32 v83, v84, v85
	v_lshlrev_b32_e32 v84, 16, v14
	v_and_b32_e32 v85, 0xffff0000, v14
	v_lshlrev_b32_e32 v86, 16, v15
	v_and_b32_e32 v87, 0xffff0000, v15
	v_pk_mul_f32 v[84:85], v[30:31], v[84:85]
	v_pk_mul_f32 v[86:87], v[30:31], v[86:87]
	v_cvt_pk_bf16_f32 v84, v84, v85
	v_cvt_pk_bf16_f32 v85, v86, v87
	s_waitcnt lgkmcnt(0)
	s_barrier
	ds_write_b128 v62, v[12:15]
	s_waitcnt vmcnt(8)
	ds_write_b128 v62, v[16:19] offset:9216
	ds_write_b128 v62, v[82:85] offset:18432
	s_waitcnt vmcnt(5)
	v_lshlrev_b32_e32 v83, 16, v56
	s_waitcnt vmcnt(4)
	v_lshlrev_b32_e32 v82, 16, v58
	v_pk_mul_f32 v[82:83], v[32:33], v[82:83]
	v_lshlrev_b32_e32 v29, 16, v54
	v_cvt_pk_bf16_f32 v81, v82, v83
	v_lshrrev_b32_e32 v82, 16, v52
	v_and_or_b32 v29, v52, s5, v29
	v_and_or_b32 v82, v54, s60, v82
	ds_write2_b32 v63, v29, v82 offset1:36
	v_and_b32_e32 v83, 0xffff0000, v56
	v_and_b32_e32 v82, 0xffff0000, v58
	v_pk_mul_f32 v[82:83], v[32:33], v[82:83]
	s_nop 0
	v_cvt_pk_bf16_f32 v29, v82, v83
	v_lshlrev_b32_e32 v83, 16, v57
	v_lshlrev_b32_e32 v82, 16, v59
	v_pk_mul_f32 v[82:83], v[32:33], v[82:83]
	ds_write2_b32 v64, v81, v29 offset1:36
	v_lshlrev_b32_e32 v29, 16, v55
	v_cvt_pk_bf16_f32 v81, v82, v83
	v_lshrrev_b32_e32 v82, 16, v53
	v_and_or_b32 v29, v53, s5, v29
	v_and_or_b32 v82, v55, s60, v82
	ds_write2_b32 v63, v29, v82 offset0:72 offset1:108
	v_and_b32_e32 v83, 0xffff0000, v57
	v_and_b32_e32 v82, 0xffff0000, v59
	v_pk_mul_f32 v[82:83], v[32:33], v[82:83]
	s_nop 0
	v_cvt_pk_bf16_f32 v29, v82, v83
	ds_write2_b32 v64, v81, v29 offset0:72 offset1:108
	s_waitcnt lgkmcnt(0)
	s_barrier
	s_cbranch_vccnz .LBB0_564
	s_add_i32 s5, s4, 64
	s_add_i32 s18, s2, 0xffffff40
	s_and_b64 s[16:17], s[8:9], exec
	s_cselect_b32 s5, s5, s18
	s_add_i32 s5, s5, s1
	v_add_u32_e32 v12, s5, v60
	v_add_u32_e32 v29, s5, v67
	v_mul_u32_u24_e32 v12, 0xe00, v12
	v_mad_u32_u24 v52, v29, s63, v61
	v_or_b32_e32 v12, v12, v77
	v_ashrrev_i32_e32 v53, 31, v52
	v_ashrrev_i32_e32 v13, 31, v12
	v_lshl_add_u64 v[58:59], v[52:53], 1, s[82:83]
	v_lshl_add_u64 v[16:17], v[12:13], 1, s[82:83]
	v_lshl_add_u64 v[56:57], s[10:11], 1, v[58:59]
	global_load_dwordx4 v[12:15], v[16:17], off offset:2560
	s_nop 0
	global_load_dwordx4 v[16:19], v[16:17], off offset:3072
	s_nop 0
	global_load_dwordx2 v[52:53], v[58:59], off offset:3584
	global_load_dwordx2 v[54:55], v[56:57], off offset:3584
	s_nop 0
	global_load_dwordx2 v[56:57], v[56:57], off offset:3072
	s_nop 0
	global_load_dwordx2 v[58:59], v[58:59], off offset:3072
